# conv boundary-row loop, diff-attention gain loads and weight-conversion gain loads de-serialized; diff K/V DMA issued under P.V MFMAs
# speedup vs baseline: 1.0119x; 1.0119x over previous
.LBB0_6:
	s_mul_hi_i32 s10, s22, 0x38e38e39
	s_lshr_b32 s11, s10, 31
	s_ashr_i32 s10, s10, 4
	s_add_i32 s11, s10, s11
	s_mul_i32 s14, s11, 0xfffff700
	s_lshl_b32 s10, s11, 6
	s_add_i32 s14, s17, s14
	v_add_u32_e32 v6, s10, v1
	s_ashr_i32 s15, s14, 31
	v_lshl_add_u64 v[16:17], s[14:15], 2, v[2:3]
	v_add_u32_e32 v7, 2, v6
	v_mad_i64_i32 v[20:21], s[14:15], v7, s19, v[16:17]
	v_add_u32_e32 v7, 4, v6
	v_mad_i64_i32 v[22:23], s[14:15], v7, s19, v[16:17]
	v_add_u32_e32 v7, 6, v6
	v_mad_i64_i32 v[24:25], s[14:15], v7, s19, v[16:17]
	v_add_u32_e32 v7, 8, v6
	v_mad_i64_i32 v[26:27], s[14:15], v7, s19, v[16:17]
	v_add_u32_e32 v7, 10, v6
	v_mad_i64_i32 v[28:29], s[14:15], v7, s19, v[16:17]
	v_add_u32_e32 v7, 12, v6
	v_mad_i64_i32 v[30:31], s[14:15], v7, s19, v[16:17]
	v_add_u32_e32 v7, 14, v6
	v_mad_i64_i32 v[18:19], s[14:15], v6, s19, v[16:17]
	v_mad_i64_i32 v[32:33], s[14:15], v7, s19, v[16:17]
	v_add_u32_e32 v7, 16, v6
	global_load_dword v44, v[18:19], off nt
	global_load_dword v46, v[20:21], off nt
	global_load_dword v45, v[22:23], off nt
	global_load_dword v43, v[24:25], off nt
	global_load_dword v40, v[26:27], off nt
	global_load_dword v42, v[28:29], off nt
	global_load_dword v41, v[30:31], off nt
	global_load_dword v39, v[32:33], off nt
	v_mad_i64_i32 v[18:19], s[14:15], v7, s19, v[16:17]
	v_add_u32_e32 v7, 18, v6
	v_mad_i64_i32 v[20:21], s[14:15], v7, s19, v[16:17]
	v_add_u32_e32 v7, 20, v6
	v_mad_i64_i32 v[22:23], s[14:15], v7, s19, v[16:17]
	v_add_u32_e32 v7, 22, v6
	v_mad_i64_i32 v[24:25], s[14:15], v7, s19, v[16:17]
	v_add_u32_e32 v7, 24, v6
	v_mad_i64_i32 v[26:27], s[14:15], v7, s19, v[16:17]
	v_add_u32_e32 v7, 26, v6
	v_mad_i64_i32 v[28:29], s[14:15], v7, s19, v[16:17]
	v_add_u32_e32 v7, 28, v6
	v_mad_i64_i32 v[48:49], s[14:15], v7, s19, v[16:17]
	v_add_u32_e32 v7, 30, v6
	v_mad_i64_i32 v[50:51], s[14:15], v7, s19, v[16:17]
	v_add_u32_e32 v7, 32, v6
	global_load_dword v36, v[18:19], off nt
	global_load_dword v38, v[20:21], off nt
	global_load_dword v37, v[22:23], off nt
	global_load_dword v35, v[24:25], off nt
	global_load_dword v32, v[26:27], off nt
	global_load_dword v34, v[28:29], off nt
	global_load_dword v33, v[48:49], off nt
	global_load_dword v31, v[50:51], off nt
	v_mad_i64_i32 v[18:19], s[14:15], v7, s19, v[16:17]
	v_add_u32_e32 v7, 34, v6
	v_mad_i64_i32 v[20:21], s[14:15], v7, s19, v[16:17]
	v_add_u32_e32 v7, 36, v6
	v_mad_i64_i32 v[48:49], s[14:15], v7, s19, v[16:17]
	v_add_u32_e32 v7, 38, v6
	v_mad_i64_i32 v[50:51], s[14:15], v7, s19, v[16:17]
	v_add_u32_e32 v7, 40, v6
	v_mad_i64_i32 v[52:53], s[14:15], v7, s19, v[16:17]
	v_add_u32_e32 v7, 42, v6
	v_mad_i64_i32 v[54:55], s[14:15], v7, s19, v[16:17]
	v_add_u32_e32 v7, 44, v6
	v_mad_i64_i32 v[56:57], s[14:15], v7, s19, v[16:17]
	v_add_u32_e32 v7, 46, v6
	v_mad_i64_i32 v[58:59], s[14:15], v7, s19, v[16:17]
	v_add_u32_e32 v7, 48, v6
	global_load_dword v28, v[18:19], off nt
	global_load_dword v30, v[20:21], off nt
	global_load_dword v29, v[48:49], off nt
	global_load_dword v27, v[50:51], off nt
	global_load_dword v24, v[52:53], off nt
	global_load_dword v26, v[54:55], off nt
	global_load_dword v25, v[56:57], off nt
	global_load_dword v23, v[58:59], off nt
	v_mad_i64_i32 v[48:49], s[14:15], v7, s19, v[16:17]
	v_add_u32_e32 v7, 50, v6
	v_mad_i64_i32 v[50:51], s[14:15], v7, s19, v[16:17]
	v_add_u32_e32 v7, 52, v6
	v_mad_i64_i32 v[52:53], s[14:15], v7, s19, v[16:17]
	v_add_u32_e32 v7, 54, v6
	v_mad_i64_i32 v[54:55], s[14:15], v7, s19, v[16:17]
	v_add_u32_e32 v7, 56, v6
	v_mad_i64_i32 v[56:57], s[14:15], v7, s19, v[16:17]
	v_add_u32_e32 v7, 58, v6
	v_mad_i64_i32 v[58:59], s[14:15], v7, s19, v[16:17]
	v_add_u32_e32 v7, 60, v6
	v_mad_i64_i32 v[60:61], s[14:15], v7, s19, v[16:17]
	v_add_u32_e32 v7, 62, v6
	v_mad_i64_i32 v[62:63], s[14:15], v7, s19, v[16:17]
	global_load_dword v20, v[48:49], off nt
	global_load_dword v22, v[50:51], off nt
	global_load_dword v21, v[52:53], off nt
	global_load_dword v19, v[54:55], off nt
	global_load_dword v16, v[56:57], off nt
	global_load_dword v18, v[58:59], off nt
	global_load_dword v17, v[60:61], off nt
	global_load_dword v15, v[62:63], off nt
	v_ashrrev_i32_e32 v7, 31, v6
	s_and_b64 vcc, exec, s[4:5]
	v_lshl_add_u64 v[6:7], v[6:7], 2, s[8:9]
	s_cbranch_vccnz .LBB0_29
	global_load_dword v96, v[6:7], off
	global_load_dword v97, v[6:7], off offset:8
	global_load_dword v98, v[6:7], off offset:16
	global_load_dword v99, v[6:7], off offset:24
	global_load_dword v100, v[6:7], off offset:32
	global_load_dword v101, v[6:7], off offset:40
	global_load_dword v102, v[6:7], off offset:48
	global_load_dword v103, v[6:7], off offset:56
	global_load_dword v104, v[6:7], off offset:64
	global_load_dword v105, v[6:7], off offset:72
	global_load_dword v106, v[6:7], off offset:80
	global_load_dword v107, v[6:7], off offset:88
	global_load_dword v108, v[6:7], off offset:96
	global_load_dword v109, v[6:7], off offset:104
	global_load_dword v110, v[6:7], off offset:112
	global_load_dword v111, v[6:7], off offset:120
	global_load_dword v112, v[6:7], off offset:128
	global_load_dword v113, v[6:7], off offset:136
	global_load_dword v114, v[6:7], off offset:144
	global_load_dword v115, v[6:7], off offset:152
	global_load_dword v116, v[6:7], off offset:160
	global_load_dword v117, v[6:7], off offset:168
	global_load_dword v118, v[6:7], off offset:176
	global_load_dword v119, v[6:7], off offset:184
	global_load_dword v120, v[6:7], off offset:192
	global_load_dword v121, v[6:7], off offset:200
	global_load_dword v122, v[6:7], off offset:208
	global_load_dword v123, v[6:7], off offset:216
	global_load_dword v124, v[6:7], off offset:224
	global_load_dword v125, v[6:7], off offset:232
	global_load_dword v126, v[6:7], off offset:240
	global_load_dword v127, v[6:7], off offset:248
	s_waitcnt vmcnt(0)
	v_mov_b32_e32 v48, v96
	v_mov_b32_e32 v49, v97
	v_mov_b32_e32 v50, v98
	v_mov_b32_e32 v47, v99
	s_waitcnt vmcnt(3)
	v_mul_f32_e32 v51, v44, v48
	s_waitcnt vmcnt(2)
	v_mul_f32_e32 v49, v46, v49
	s_waitcnt vmcnt(1)
	v_mul_f32_e32 v48, v45, v50
	ds_write2_b32 v10, v51, v49 offset1:66
	s_cbranch_execnz .LBB0_9

.LBB0_9:
	s_waitcnt vmcnt(0)
	v_mul_f32_e32 v43, v43, v47
	s_and_b64 vcc, exec, s[4:5]
	ds_write2_b32 v11, v48, v43 offset1:66
	s_cbranch_vccnz .LBB0_30
	v_mov_b32_e32 v44, v100
	v_mov_b32_e32 v45, v101
	v_mov_b32_e32 v46, v102
	v_mov_b32_e32 v43, v103
	s_waitcnt vmcnt(3)
	v_mul_f32_e32 v47, v40, v44
	s_waitcnt vmcnt(2)
	v_mul_f32_e32 v45, v42, v45
	s_waitcnt vmcnt(1)
	v_mul_f32_e32 v44, v41, v46
	ds_write2_b32 v13, v47, v45 offset1:66
	s_cbranch_execnz .LBB0_12

.LBB0_12:
	s_waitcnt vmcnt(0)
	v_mul_f32_e32 v39, v39, v43
	s_and_b64 vcc, exec, s[4:5]
	ds_write2_b32 v12, v44, v39 offset1:66
	s_cbranch_vccnz .LBB0_31
	v_mov_b32_e32 v40, v104
	v_mov_b32_e32 v41, v105
	v_mov_b32_e32 v42, v106
	v_mov_b32_e32 v39, v107
	s_waitcnt vmcnt(3)
	v_mul_f32_e32 v43, v36, v40
	s_waitcnt vmcnt(2)
	v_mul_f32_e32 v41, v38, v41
	s_waitcnt vmcnt(1)
	v_mul_f32_e32 v40, v37, v42
	ds_write2_b32 v14, v43, v41 offset1:66
	s_cbranch_execnz .LBB0_15

.LBB0_15:
	s_waitcnt vmcnt(0)
	v_mul_f32_e32 v35, v35, v39
	ds_write2_b32 v14, v40, v35 offset0:132 offset1:198
	s_and_b64 vcc, exec, s[4:5]
	v_add_u32_e32 v35, 0x400, v14
	s_cbranch_vccnz .LBB0_32
	v_mov_b32_e32 v37, v108
	v_mov_b32_e32 v38, v109
	v_mov_b32_e32 v39, v110
	v_mov_b32_e32 v36, v111
	s_waitcnt vmcnt(3)
	v_mul_f32_e32 v40, v32, v37
	s_waitcnt vmcnt(2)
	v_mul_f32_e32 v38, v34, v38
	s_waitcnt vmcnt(1)
	v_mul_f32_e32 v37, v33, v39
	ds_write2_b32 v35, v40, v38 offset0:8 offset1:74
	s_cbranch_execnz .LBB0_18

.LBB0_18:
	s_waitcnt vmcnt(0)
	v_mul_f32_e32 v31, v31, v36
	ds_write2_b32 v35, v37, v31 offset0:140 offset1:206
	s_and_b64 vcc, exec, s[4:5]
	v_add_u32_e32 v31, 0x800, v14
	s_cbranch_vccnz .LBB0_33
	v_mov_b32_e32 v33, v112
	v_mov_b32_e32 v34, v113
	v_mov_b32_e32 v35, v114
	v_mov_b32_e32 v32, v115
	s_waitcnt vmcnt(3)
	v_mul_f32_e32 v36, v28, v33
	s_waitcnt vmcnt(2)
	v_mul_f32_e32 v34, v30, v34
	s_waitcnt vmcnt(1)
	v_mul_f32_e32 v33, v29, v35
	ds_write2_b32 v31, v36, v34 offset0:16 offset1:82
	s_cbranch_execnz .LBB0_21

.LBB0_21:
	s_waitcnt vmcnt(0)
	v_mul_f32_e32 v27, v27, v32
	ds_write2_b32 v31, v33, v27 offset0:148 offset1:214
	s_and_b64 vcc, exec, s[4:5]
	v_add_u32_e32 v27, 0xc00, v14
	s_cbranch_vccnz .LBB0_34
	v_mov_b32_e32 v29, v116
	v_mov_b32_e32 v30, v117
	v_mov_b32_e32 v31, v118
	v_mov_b32_e32 v28, v119
	s_waitcnt vmcnt(3)
	v_mul_f32_e32 v32, v24, v29
	s_waitcnt vmcnt(2)
	v_mul_f32_e32 v30, v26, v30
	s_waitcnt vmcnt(1)
	v_mul_f32_e32 v29, v25, v31
	ds_write2_b32 v27, v32, v30 offset0:24 offset1:90
	s_cbranch_execnz .LBB0_24

.LBB0_24:
	s_waitcnt vmcnt(0)
	v_mul_f32_e32 v23, v23, v28
	ds_write2_b32 v27, v29, v23 offset0:156 offset1:222
	s_and_b64 vcc, exec, s[4:5]
	v_add_u32_e32 v23, 0x1000, v14
	s_cbranch_vccnz .LBB0_35
	v_mov_b32_e32 v25, v120
	v_mov_b32_e32 v26, v121
	v_mov_b32_e32 v27, v122
	v_mov_b32_e32 v24, v123
	s_waitcnt vmcnt(3)
	v_mul_f32_e32 v28, v20, v25
	s_waitcnt vmcnt(2)
	v_mul_f32_e32 v26, v22, v26
	s_waitcnt vmcnt(1)
	v_mul_f32_e32 v25, v21, v27
	ds_write2_b32 v23, v28, v26 offset0:32 offset1:98
	s_cbranch_execnz .LBB0_27

.LBB0_27:
	s_waitcnt vmcnt(0)
	v_mul_f32_e32 v19, v19, v24
	ds_write2_b32 v23, v25, v19 offset0:164 offset1:230
	s_and_b64 vcc, exec, s[4:5]
	v_add_u32_e32 v19, 0x1400, v14
	s_cbranch_vccnz .LBB0_36
	v_mov_b32_e32 v21, v124
	v_mov_b32_e32 v22, v125
	v_mov_b32_e32 v23, v126
	v_mov_b32_e32 v20, v127
	s_waitcnt vmcnt(3)
	v_mul_f32_e32 v7, v16, v21
	s_waitcnt vmcnt(2)
	v_mul_f32_e32 v21, v18, v22
	s_waitcnt vmcnt(1)
	v_mul_f32_e32 v6, v17, v23
	ds_write2_b32 v19, v7, v21 offset0:40 offset1:106
	s_cbranch_execnz .LBB0_5
	s_branch .LBB0_37

.LBB0_127:
	s_andn2_b64 vcc, exec, s[0:1]
	s_cbranch_vccnz .LBB0_153
	s_add_i32 s0, s17, 0xf980
	s_and_b32 s1, s0, 0xffff
	s_mul_i32 s1, s1, 0xba2f
	s_lshr_b32 s1, s1, 23
	s_load_dwordx4 s[40:43], s[48:49], 0x70
	s_mul_i32 s4, s1, 0xb0
	s_sub_i32 s0, s0, s4
	s_and_b32 s7, s0, 0xffff
	s_lshl_b32 s6, s1, 6
	s_lshl_b32 s0, s7, 7
	s_waitcnt lgkmcnt(0)
	s_add_u32 s0, s42, s0
	s_addc_u32 s1, s43, 0
	v_lshlrev_b32_e32 v0, 2, v2
	v_add_u32_e32 v12, s6, v3
	v_lshl_add_u64 v[64:65], s[0:1], 0, v[0:1]
	s_movk_i32 s4, 0x5800
	v_mad_i64_i32 v[32:33], s[0:1], v12, s4, v[64:65]
	v_add_u32_e32 v0, 2, v12
	global_load_dword v59, v[32:33], off nt
	v_mad_i64_i32 v[32:33], s[0:1], v0, s4, v[64:65]
	v_add_u32_e32 v0, 4, v12
	global_load_dword v60, v[32:33], off nt
	v_mad_i64_i32 v[32:33], s[0:1], v0, s4, v[64:65]
	v_add_u32_e32 v0, 6, v12
	global_load_dword v62, v[32:33], off nt
	v_mad_i64_i32 v[32:33], s[0:1], v0, s4, v[64:65]
	v_add_u32_e32 v0, 8, v12
	global_load_dword v61, v[32:33], off nt
	v_mad_i64_i32 v[32:33], s[0:1], v0, s4, v[64:65]
	v_add_u32_e32 v0, 10, v12
	global_load_dword v55, v[32:33], off nt
	v_mad_i64_i32 v[32:33], s[0:1], v0, s4, v[64:65]
	v_add_u32_e32 v0, 12, v12
	global_load_dword v56, v[32:33], off nt
	v_mad_i64_i32 v[32:33], s[0:1], v0, s4, v[64:65]
	v_add_u32_e32 v0, 14, v12
	global_load_dword v57, v[32:33], off nt
	v_mad_i64_i32 v[32:33], s[0:1], v0, s4, v[64:65]
	v_add_u32_e32 v0, 16, v12
	global_load_dword v58, v[32:33], off nt
	v_mad_i64_i32 v[32:33], s[0:1], v0, s4, v[64:65]
	v_add_u32_e32 v0, 18, v12
	global_load_dword v51, v[32:33], off nt
	v_mad_i64_i32 v[32:33], s[0:1], v0, s4, v[64:65]
	v_add_u32_e32 v0, 20, v12
	global_load_dword v52, v[32:33], off nt
	v_mad_i64_i32 v[32:33], s[0:1], v0, s4, v[64:65]
	v_add_u32_e32 v0, 22, v12
	global_load_dword v53, v[32:33], off nt
	v_mad_i64_i32 v[32:33], s[0:1], v0, s4, v[64:65]
	v_add_u32_e32 v0, 24, v12
	global_load_dword v54, v[32:33], off nt
	v_mad_i64_i32 v[32:33], s[0:1], v0, s4, v[64:65]
	v_add_u32_e32 v0, 26, v12
	global_load_dword v47, v[32:33], off nt
	v_mad_i64_i32 v[32:33], s[0:1], v0, s4, v[64:65]
	v_add_u32_e32 v0, 28, v12
	global_load_dword v48, v[32:33], off nt
	v_mad_i64_i32 v[32:33], s[0:1], v0, s4, v[64:65]
	v_add_u32_e32 v0, 30, v12
	global_load_dword v49, v[32:33], off nt
	v_mad_i64_i32 v[32:33], s[0:1], v0, s4, v[64:65]
	v_add_u32_e32 v0, 32, v12
	global_load_dword v50, v[32:33], off nt
	v_mad_i64_i32 v[32:33], s[0:1], v0, s4, v[64:65]
	v_add_u32_e32 v0, 34, v12
	global_load_dword v43, v[32:33], off nt
	v_mad_i64_i32 v[32:33], s[0:1], v0, s4, v[64:65]
	v_add_u32_e32 v0, 36, v12
	global_load_dword v44, v[32:33], off nt
	v_mad_i64_i32 v[32:33], s[0:1], v0, s4, v[64:65]
	v_add_u32_e32 v0, 38, v12
	global_load_dword v45, v[32:33], off nt
	v_mad_i64_i32 v[32:33], s[0:1], v0, s4, v[64:65]
	v_add_u32_e32 v0, 40, v12
	global_load_dword v46, v[32:33], off nt
	v_mad_i64_i32 v[32:33], s[0:1], v0, s4, v[64:65]
	v_add_u32_e32 v0, 42, v12
	global_load_dword v39, v[32:33], off nt
	v_mad_i64_i32 v[32:33], s[0:1], v0, s4, v[64:65]
	v_add_u32_e32 v0, 44, v12
	global_load_dword v40, v[32:33], off nt
	v_mad_i64_i32 v[32:33], s[0:1], v0, s4, v[64:65]
	v_add_u32_e32 v0, 46, v12
	global_load_dword v41, v[32:33], off nt
	v_mad_i64_i32 v[32:33], s[0:1], v0, s4, v[64:65]
	v_add_u32_e32 v0, 48, v12
	global_load_dword v42, v[32:33], off nt
	v_mad_i64_i32 v[32:33], s[0:1], v0, s4, v[64:65]
	v_add_u32_e32 v0, 50, v12
	global_load_dword v35, v[32:33], off nt
	v_mad_i64_i32 v[32:33], s[0:1], v0, s4, v[64:65]
	v_add_u32_e32 v0, 52, v12
	global_load_dword v36, v[32:33], off nt
	v_mad_i64_i32 v[32:33], s[0:1], v0, s4, v[64:65]
	v_add_u32_e32 v0, 54, v12
	global_load_dword v37, v[32:33], off nt
	v_mad_i64_i32 v[32:33], s[0:1], v0, s4, v[64:65]
	v_add_u32_e32 v0, 56, v12
	global_load_dword v38, v[32:33], off nt
	v_mad_i64_i32 v[32:33], s[0:1], v0, s4, v[64:65]
	v_add_u32_e32 v13, 58, v12
	global_load_dword v0, v[32:33], off nt
	v_mad_i64_i32 v[32:33], s[0:1], v13, s4, v[64:65]
	v_add_u32_e32 v13, 60, v12
	v_mad_i64_i32 v[66:67], s[0:1], v13, s4, v[64:65]
	v_add_u32_e32 v13, 62, v12
	v_mad_i64_i32 v[64:65], s[0:1], v13, s4, v[64:65]
	global_load_dword v32, v[32:33], off nt
	v_ashrrev_i32_e32 v13, 31, v12
	global_load_dword v34, v[64:65], off nt
	global_load_dword v33, v[66:67], off nt
	s_cmp_lg_u64 s[40:41], 0
	s_cselect_b64 s[0:1], -1, 0
	s_cmp_eq_u64 s[40:41], 0
	v_lshl_add_u64 v[12:13], v[12:13], 2, s[40:41]
	s_cbranch_scc1 .LBB0_190
	global_load_dword v96, v[12:13], off
	global_load_dword v97, v[12:13], off offset:8
	global_load_dword v98, v[12:13], off offset:16
	global_load_dword v99, v[12:13], off offset:24
	global_load_dword v100, v[12:13], off offset:32
	global_load_dword v101, v[12:13], off offset:40
	global_load_dword v102, v[12:13], off offset:48
	global_load_dword v103, v[12:13], off offset:56
	global_load_dword v104, v[12:13], off offset:64
	global_load_dword v105, v[12:13], off offset:72
	global_load_dword v106, v[12:13], off offset:80
	global_load_dword v107, v[12:13], off offset:88
	global_load_dword v108, v[12:13], off offset:96
	global_load_dword v109, v[12:13], off offset:104
	global_load_dword v110, v[12:13], off offset:112
	global_load_dword v111, v[12:13], off offset:120
	global_load_dword v112, v[12:13], off offset:128
	global_load_dword v113, v[12:13], off offset:136
	global_load_dword v114, v[12:13], off offset:144
	global_load_dword v115, v[12:13], off offset:152
	global_load_dword v116, v[12:13], off offset:160
	global_load_dword v117, v[12:13], off offset:168
	global_load_dword v118, v[12:13], off offset:176
	global_load_dword v119, v[12:13], off offset:184
	global_load_dword v120, v[12:13], off offset:192
	global_load_dword v121, v[12:13], off offset:200
	global_load_dword v122, v[12:13], off offset:208
	global_load_dword v123, v[12:13], off offset:216
	global_load_dword v124, v[12:13], off offset:224
	global_load_dword v125, v[12:13], off offset:232
	global_load_dword v126, v[12:13], off offset:240
	global_load_dword v127, v[12:13], off offset:248
	s_waitcnt vmcnt(0)
	v_mov_b32_e32 v63, v96
	v_mov_b32_e32 v64, v97
	v_add_u32_e32 v65, v14, v15
	s_waitcnt vmcnt(0)
	v_mul_f32_e32 v63, v59, v63
	ds_write_b32 v65, v63
	v_mul_f32_e32 v63, v60, v64
	v_add_u32_e32 v64, v14, v21
	ds_write_b32 v64, v63
	v_mov_b32_e32 v63, v98
	v_mov_b32_e32 v64, v99
	s_waitcnt vmcnt(1)
	v_mul_f32_e32 v63, v62, v63
	s_cbranch_execnz .LBB0_131

.LBB0_131:
	s_waitcnt vmcnt(0)
	v_mul_f32_e32 v60, v61, v64
	v_cndmask_b32_e64 v61, 0, 1, s[0:1]
	v_add_u32_e32 v59, v14, v22
	v_cmp_ne_u32_e64 s[40:41], 1, v61
	s_andn2_b64 vcc, exec, s[0:1]
	ds_write2_b32 v59, v63, v60 offset1:66
	s_cbranch_vccnz .LBB0_191
	v_mov_b32_e32 v59, v100
	v_mov_b32_e32 v60, v101
	v_add_u32_e32 v61, v14, v23
	s_waitcnt vmcnt(1)
	v_mul_f32_e32 v59, v55, v59
	s_waitcnt vmcnt(0)
	v_mul_f32_e32 v60, v56, v60
	ds_write2_b32 v61, v59, v60 offset1:66
	v_mov_b32_e32 v59, v102
	v_mov_b32_e32 v60, v103
	s_waitcnt vmcnt(1)
	v_mul_f32_e32 v59, v57, v59
	s_cbranch_execnz .LBB0_134

.LBB0_134:
	v_add_u32_e32 v55, v14, v24
	s_waitcnt vmcnt(0)
	v_mul_f32_e32 v56, v58, v60
	s_and_b64 vcc, exec, s[40:41]
	ds_write2_b32 v55, v59, v56 offset1:66
	s_cbranch_vccnz .LBB0_192
	v_mov_b32_e32 v55, v104
	v_mov_b32_e32 v56, v105
	v_add_u32_e32 v57, v14, v25
	s_waitcnt vmcnt(1)
	v_mul_f32_e32 v55, v51, v55
	s_waitcnt vmcnt(0)
	v_mul_f32_e32 v56, v52, v56
	ds_write2_b32 v57, v55, v56 offset1:66
	v_mov_b32_e32 v55, v106
	v_mov_b32_e32 v56, v107
	s_waitcnt vmcnt(1)
	v_mul_f32_e32 v55, v53, v55
	s_cbranch_execnz .LBB0_137

.LBB0_137:
	v_add_u32_e32 v51, v14, v26
	s_waitcnt vmcnt(0)
	v_mul_f32_e32 v52, v54, v56
	s_and_b64 vcc, exec, s[40:41]
	ds_write2_b32 v51, v55, v52 offset1:66
	s_cbranch_vccnz .LBB0_193
	v_mov_b32_e32 v51, v108
	v_mov_b32_e32 v52, v109
	v_add_u32_e32 v53, v14, v27
	s_waitcnt vmcnt(1)
	v_mul_f32_e32 v51, v47, v51
	s_waitcnt vmcnt(0)
	v_mul_f32_e32 v52, v48, v52
	ds_write2_b32 v53, v51, v52 offset1:66
	v_mov_b32_e32 v51, v110
	v_mov_b32_e32 v52, v111
	s_waitcnt vmcnt(1)
	v_mul_f32_e32 v51, v49, v51
	s_cbranch_execnz .LBB0_140

.LBB0_140:
	v_add_u32_e32 v47, v14, v28
	s_waitcnt vmcnt(0)
	v_mul_f32_e32 v48, v50, v52
	s_and_b64 vcc, exec, s[40:41]
	ds_write2_b32 v47, v51, v48 offset1:66
	s_cbranch_vccnz .LBB0_194
	v_mov_b32_e32 v47, v112
	v_mov_b32_e32 v48, v113
	v_add_u32_e32 v49, v14, v29
	s_waitcnt vmcnt(1)
	v_mul_f32_e32 v47, v43, v47
	s_waitcnt vmcnt(0)
	v_mul_f32_e32 v48, v44, v48
	ds_write2_b32 v49, v47, v48 offset1:66
	v_mov_b32_e32 v47, v114
	v_mov_b32_e32 v48, v115
	s_waitcnt vmcnt(1)
	v_mul_f32_e32 v47, v45, v47
	s_cbranch_execnz .LBB0_143

.LBB0_143:
	v_add_u32_e32 v43, v14, v30
	s_waitcnt vmcnt(0)
	v_mul_f32_e32 v44, v46, v48
	s_and_b64 vcc, exec, s[40:41]
	ds_write2_b32 v43, v47, v44 offset1:66
	s_cbranch_vccnz .LBB0_195
	v_mov_b32_e32 v43, v116
	v_mov_b32_e32 v44, v117
	v_add_u32_e32 v45, v14, v31
	s_waitcnt vmcnt(1)
	v_mul_f32_e32 v43, v39, v43
	s_waitcnt vmcnt(0)
	v_mul_f32_e32 v44, v40, v44
	ds_write2_b32 v45, v43, v44 offset1:66
	v_mov_b32_e32 v43, v118
	v_mov_b32_e32 v44, v119
	s_waitcnt vmcnt(1)
	v_mul_f32_e32 v43, v41, v43
	s_cbranch_execnz .LBB0_146

.LBB0_146:
	v_add_u32_e32 v39, v14, v31
	s_waitcnt vmcnt(0)
	v_mul_f32_e32 v40, v42, v44
	ds_write2_b32 v39, v43, v40 offset0:132 offset1:198
	s_and_b64 vcc, exec, s[40:41]
	v_add_u32_e32 v40, 0x400, v39
	s_cbranch_vccnz .LBB0_196
	v_mov_b32_e32 v41, v120
	v_mov_b32_e32 v42, v121
	s_waitcnt vmcnt(1)
	v_mul_f32_e32 v41, v35, v41
	s_waitcnt vmcnt(0)
	v_mul_f32_e32 v42, v36, v42
	ds_write2_b32 v40, v41, v42 offset0:8 offset1:74
	v_mov_b32_e32 v41, v122
	v_mov_b32_e32 v42, v123
	s_waitcnt vmcnt(1)
	v_mul_f32_e32 v41, v37, v41
	s_cbranch_execnz .LBB0_149

.LBB0_149:
	s_waitcnt vmcnt(0)
	v_mul_f32_e32 v35, v38, v42
	ds_write2_b32 v40, v41, v35 offset0:140 offset1:206
	s_and_b64 vcc, exec, s[40:41]
	v_add_u32_e32 v35, 0x800, v39
	s_cbranch_vccnz .LBB0_197
	v_mov_b32_e32 v36, v124
	v_mov_b32_e32 v37, v125
	s_waitcnt vmcnt(1)
	v_mul_f32_e32 v36, v0, v36
	s_waitcnt vmcnt(0)
	v_mul_f32_e32 v37, v32, v37
	ds_write2_b32 v35, v36, v37 offset0:16 offset1:82
	v_mov_b32_e32 v36, v126
	s_waitcnt vmcnt(0)
	v_mul_f32_e32 v36, v33, v36
	v_mov_b32_e32 v12, v127
	s_cbranch_execnz .LBB0_152

.LBB0_157:
	s_andn2_b64 vcc, exec, s[0:1]
	s_cbranch_vccnz .LBB0_122
	s_mul_hi_i32 s0, s17, 0x38e38e39
	s_lshr_b32 s1, s0, 31
	s_ashr_i32 s0, s0, 4
	s_add_i32 s1, s0, s1
	s_load_dwordx4 s[40:43], s[48:49], 0x8
	s_mul_i32 s4, s1, 0xfffff700
	s_add_i32 s4, s11, s4
	s_ashr_i32 s5, s4, 31
	s_lshl_b32 s0, s1, 6
	s_lshl_b64 s[4:5], s[4:5], 2
	s_waitcnt lgkmcnt(0)
	s_add_u32 s4, s42, s4
	s_addc_u32 s5, s43, s5
	v_lshlrev_b32_e32 v0, 2, v2
	v_add_u32_e32 v12, s0, v3
	v_lshl_add_u64 v[64:65], s[4:5], 0, v[0:1]
	v_mad_i64_i32 v[32:33], s[4:5], v12, s95, v[64:65]
	v_add_u32_e32 v0, 2, v12
	global_load_dword v59, v[32:33], off nt
	v_mad_i64_i32 v[32:33], s[4:5], v0, s95, v[64:65]
	v_add_u32_e32 v0, 4, v12
	global_load_dword v60, v[32:33], off nt
	v_mad_i64_i32 v[32:33], s[4:5], v0, s95, v[64:65]
	v_add_u32_e32 v0, 6, v12
	global_load_dword v62, v[32:33], off nt
	v_mad_i64_i32 v[32:33], s[4:5], v0, s95, v[64:65]
	v_add_u32_e32 v0, 8, v12
	global_load_dword v61, v[32:33], off nt
	v_mad_i64_i32 v[32:33], s[4:5], v0, s95, v[64:65]
	v_add_u32_e32 v0, 10, v12
	global_load_dword v55, v[32:33], off nt
	v_mad_i64_i32 v[32:33], s[4:5], v0, s95, v[64:65]
	v_add_u32_e32 v0, 12, v12
	global_load_dword v56, v[32:33], off nt
	v_mad_i64_i32 v[32:33], s[4:5], v0, s95, v[64:65]
	v_add_u32_e32 v0, 14, v12
	global_load_dword v57, v[32:33], off nt
	v_mad_i64_i32 v[32:33], s[4:5], v0, s95, v[64:65]
	v_add_u32_e32 v0, 16, v12
	global_load_dword v58, v[32:33], off nt
	v_mad_i64_i32 v[32:33], s[4:5], v0, s95, v[64:65]
	v_add_u32_e32 v0, 18, v12
	global_load_dword v51, v[32:33], off nt
	v_mad_i64_i32 v[32:33], s[4:5], v0, s95, v[64:65]
	v_add_u32_e32 v0, 20, v12
	global_load_dword v52, v[32:33], off nt
	v_mad_i64_i32 v[32:33], s[4:5], v0, s95, v[64:65]
	v_add_u32_e32 v0, 22, v12
	global_load_dword v53, v[32:33], off nt
	v_mad_i64_i32 v[32:33], s[4:5], v0, s95, v[64:65]
	v_add_u32_e32 v0, 24, v12
	global_load_dword v54, v[32:33], off nt
	v_mad_i64_i32 v[32:33], s[4:5], v0, s95, v[64:65]
	v_add_u32_e32 v0, 26, v12
	global_load_dword v47, v[32:33], off nt
	v_mad_i64_i32 v[32:33], s[4:5], v0, s95, v[64:65]
	v_add_u32_e32 v0, 28, v12
	global_load_dword v48, v[32:33], off nt
	v_mad_i64_i32 v[32:33], s[4:5], v0, s95, v[64:65]
	v_add_u32_e32 v0, 30, v12
	global_load_dword v49, v[32:33], off nt
	v_mad_i64_i32 v[32:33], s[4:5], v0, s95, v[64:65]
	v_add_u32_e32 v0, 32, v12
	global_load_dword v50, v[32:33], off nt
	v_mad_i64_i32 v[32:33], s[4:5], v0, s95, v[64:65]
	v_add_u32_e32 v0, 34, v12
	global_load_dword v43, v[32:33], off nt
	v_mad_i64_i32 v[32:33], s[4:5], v0, s95, v[64:65]
	v_add_u32_e32 v0, 36, v12
	global_load_dword v44, v[32:33], off nt
	v_mad_i64_i32 v[32:33], s[4:5], v0, s95, v[64:65]
	v_add_u32_e32 v0, 38, v12
	global_load_dword v45, v[32:33], off nt
	v_mad_i64_i32 v[32:33], s[4:5], v0, s95, v[64:65]
	v_add_u32_e32 v0, 40, v12
	global_load_dword v46, v[32:33], off nt
	v_mad_i64_i32 v[32:33], s[4:5], v0, s95, v[64:65]
	v_add_u32_e32 v0, 42, v12
	global_load_dword v39, v[32:33], off nt
	v_mad_i64_i32 v[32:33], s[4:5], v0, s95, v[64:65]
	v_add_u32_e32 v0, 44, v12
	global_load_dword v40, v[32:33], off nt
	v_mad_i64_i32 v[32:33], s[4:5], v0, s95, v[64:65]
	v_add_u32_e32 v0, 46, v12
	global_load_dword v41, v[32:33], off nt
	v_mad_i64_i32 v[32:33], s[4:5], v0, s95, v[64:65]
	v_add_u32_e32 v0, 48, v12
	global_load_dword v42, v[32:33], off nt
	v_mad_i64_i32 v[32:33], s[4:5], v0, s95, v[64:65]
	v_add_u32_e32 v0, 50, v12
	global_load_dword v35, v[32:33], off nt
	v_mad_i64_i32 v[32:33], s[4:5], v0, s95, v[64:65]
	v_add_u32_e32 v0, 52, v12
	global_load_dword v36, v[32:33], off nt
	v_mad_i64_i32 v[32:33], s[4:5], v0, s95, v[64:65]
	v_add_u32_e32 v0, 54, v12
	global_load_dword v37, v[32:33], off nt
	v_mad_i64_i32 v[32:33], s[4:5], v0, s95, v[64:65]
	v_add_u32_e32 v0, 56, v12
	global_load_dword v38, v[32:33], off nt
	v_mad_i64_i32 v[32:33], s[4:5], v0, s95, v[64:65]
	global_load_dword v0, v[32:33], off nt
	v_add_u32_e32 v32, 58, v12
	v_mad_i64_i32 v[32:33], s[4:5], v32, s95, v[64:65]
	global_load_dword v32, v[32:33], off nt
	v_add_u32_e32 v33, 60, v12
	v_add_u32_e32 v34, 62, v12
	v_mad_i64_i32 v[66:67], s[4:5], v33, s95, v[64:65]
	v_mad_i64_i32 v[64:65], s[4:5], v34, s95, v[64:65]
	global_load_dword v33, v[66:67], off nt
	global_load_dword v34, v[64:65], off nt
	v_ashrrev_i32_e32 v13, 31, v12
	s_cmp_lg_u64 s[40:41], 0
	s_cselect_b64 s[4:5], -1, 0
	s_cmp_eq_u64 s[40:41], 0
	v_add_u32_e32 v63, v14, v15
	v_add_u32_e32 v64, v14, v21
	v_lshl_add_u64 v[12:13], v[12:13], 2, s[40:41]
	s_cbranch_scc1 .LBB0_181
	global_load_dword v96, v[12:13], off
	global_load_dword v97, v[12:13], off offset:8
	global_load_dword v98, v[12:13], off offset:16
	global_load_dword v99, v[12:13], off offset:24
	global_load_dword v100, v[12:13], off offset:32
	global_load_dword v101, v[12:13], off offset:40
	global_load_dword v102, v[12:13], off offset:48
	global_load_dword v103, v[12:13], off offset:56
	global_load_dword v104, v[12:13], off offset:64
	global_load_dword v105, v[12:13], off offset:72
	global_load_dword v106, v[12:13], off offset:80
	global_load_dword v107, v[12:13], off offset:88
	global_load_dword v108, v[12:13], off offset:96
	global_load_dword v109, v[12:13], off offset:104
	global_load_dword v110, v[12:13], off offset:112
	global_load_dword v111, v[12:13], off offset:120
	global_load_dword v112, v[12:13], off offset:128
	global_load_dword v113, v[12:13], off offset:136
	global_load_dword v114, v[12:13], off offset:144
	global_load_dword v115, v[12:13], off offset:152
	global_load_dword v116, v[12:13], off offset:160
	global_load_dword v117, v[12:13], off offset:168
	global_load_dword v118, v[12:13], off offset:176
	global_load_dword v119, v[12:13], off offset:184
	global_load_dword v120, v[12:13], off offset:192
	global_load_dword v121, v[12:13], off offset:200
	global_load_dword v122, v[12:13], off offset:208
	global_load_dword v123, v[12:13], off offset:216
	global_load_dword v124, v[12:13], off offset:224
	global_load_dword v125, v[12:13], off offset:232
	global_load_dword v126, v[12:13], off offset:240
	global_load_dword v127, v[12:13], off offset:248
	s_waitcnt vmcnt(0)
	v_mov_b32_e32 v65, v96
	v_mov_b32_e32 v66, v97
	s_waitcnt vmcnt(0)
	v_mul_f32_e32 v65, v59, v65
	ds_write_b32 v63, v65
	v_mul_f32_e32 v65, v60, v66
	ds_write_b32 v64, v65
	v_mov_b32_e32 v65, v98
	v_mov_b32_e32 v66, v99
	s_waitcnt vmcnt(1)
	v_mul_f32_e32 v65, v62, v65
	s_cbranch_execnz .LBB0_161

.LBB0_161:
	s_waitcnt vmcnt(0)
	v_add_u32_e32 v59, v14, v22
	v_mul_f32_e32 v60, v61, v66
	ds_write2_b32 v59, v65, v60 offset1:66
	v_cndmask_b32_e64 v59, 0, 1, s[4:5]
	v_cmp_ne_u32_e64 s[40:41], 1, v59
	s_andn2_b64 vcc, exec, s[4:5]
	v_add_u32_e32 v59, v14, v23
	s_cbranch_vccnz .LBB0_182
	v_mov_b32_e32 v60, v100
	v_mov_b32_e32 v61, v101
	s_waitcnt vmcnt(1)
	v_mul_f32_e32 v60, v55, v60
	s_waitcnt vmcnt(0)
	v_mul_f32_e32 v61, v56, v61
	ds_write2_b32 v59, v60, v61 offset1:66
	v_mov_b32_e32 v60, v102
	v_mov_b32_e32 v61, v103
	s_waitcnt vmcnt(1)
	v_mul_f32_e32 v60, v57, v60
	s_cbranch_execnz .LBB0_164

.LBB0_164:
	v_add_u32_e32 v55, v14, v24
	s_waitcnt vmcnt(0)
	v_mul_f32_e32 v56, v58, v61
	ds_write2_b32 v55, v60, v56 offset1:66
	s_and_b64 vcc, exec, s[40:41]
	v_add_u32_e32 v55, v14, v25
	s_cbranch_vccnz .LBB0_183
	v_mov_b32_e32 v56, v104
	v_mov_b32_e32 v57, v105
	s_waitcnt vmcnt(1)
	v_mul_f32_e32 v56, v51, v56
	s_waitcnt vmcnt(0)
	v_mul_f32_e32 v57, v52, v57
	ds_write2_b32 v55, v56, v57 offset1:66
	v_mov_b32_e32 v56, v106
	v_mov_b32_e32 v57, v107
	s_waitcnt vmcnt(1)
	v_mul_f32_e32 v56, v53, v56
	s_cbranch_execnz .LBB0_167

.LBB0_167:
	v_add_u32_e32 v51, v14, v26
	s_waitcnt vmcnt(0)
	v_mul_f32_e32 v52, v54, v57
	ds_write2_b32 v51, v56, v52 offset1:66
	s_and_b64 vcc, exec, s[40:41]
	v_add_u32_e32 v51, v14, v27
	s_cbranch_vccnz .LBB0_184
	v_mov_b32_e32 v52, v108
	v_mov_b32_e32 v53, v109
	s_waitcnt vmcnt(1)
	v_mul_f32_e32 v52, v47, v52
	s_waitcnt vmcnt(0)
	v_mul_f32_e32 v53, v48, v53
	ds_write2_b32 v51, v52, v53 offset1:66
	v_mov_b32_e32 v52, v110
	v_mov_b32_e32 v53, v111
	s_waitcnt vmcnt(1)
	v_mul_f32_e32 v52, v49, v52
	s_cbranch_execnz .LBB0_170

.LBB0_170:
	v_add_u32_e32 v47, v14, v28
	s_waitcnt vmcnt(0)
	v_mul_f32_e32 v48, v50, v53
	ds_write2_b32 v47, v52, v48 offset1:66
	s_and_b64 vcc, exec, s[40:41]
	v_add_u32_e32 v47, v14, v29
	s_cbranch_vccnz .LBB0_185
	v_mov_b32_e32 v48, v112
	v_mov_b32_e32 v49, v113
	s_waitcnt vmcnt(1)
	v_mul_f32_e32 v48, v43, v48
	s_waitcnt vmcnt(0)
	v_mul_f32_e32 v49, v44, v49
	ds_write2_b32 v47, v48, v49 offset1:66
	v_mov_b32_e32 v48, v114
	v_mov_b32_e32 v49, v115
	s_waitcnt vmcnt(1)
	v_mul_f32_e32 v48, v45, v48
	s_cbranch_execnz .LBB0_173

.LBB0_173:
	v_add_u32_e32 v43, v14, v30
	s_waitcnt vmcnt(0)
	v_mul_f32_e32 v44, v46, v49
	ds_write2_b32 v43, v48, v44 offset1:66
	s_and_b64 vcc, exec, s[40:41]
	v_add_u32_e32 v43, v14, v31
	s_cbranch_vccnz .LBB0_186
	v_mov_b32_e32 v44, v116
	v_mov_b32_e32 v45, v117
	s_waitcnt vmcnt(1)
	v_mul_f32_e32 v44, v39, v44
	s_waitcnt vmcnt(0)
	v_mul_f32_e32 v45, v40, v45
	ds_write2_b32 v43, v44, v45 offset1:66
	v_mov_b32_e32 v44, v118
	v_mov_b32_e32 v45, v119
	s_waitcnt vmcnt(1)
	v_mul_f32_e32 v44, v41, v44
	s_cbranch_execnz .LBB0_176

.LBB0_176:
	s_waitcnt vmcnt(0)
	v_mul_f32_e32 v39, v42, v45
	ds_write2_b32 v43, v44, v39 offset0:132 offset1:198
	s_and_b64 vcc, exec, s[40:41]
	v_add_u32_e32 v39, 0x400, v43
	s_cbranch_vccnz .LBB0_187
	v_mov_b32_e32 v40, v120
	v_mov_b32_e32 v41, v121
	s_waitcnt vmcnt(1)
	v_mul_f32_e32 v40, v35, v40
	s_waitcnt vmcnt(0)
	v_mul_f32_e32 v41, v36, v41
	ds_write2_b32 v39, v40, v41 offset0:8 offset1:74
	v_mov_b32_e32 v40, v122
	v_mov_b32_e32 v41, v123
	s_waitcnt vmcnt(1)
	v_mul_f32_e32 v40, v37, v40
	s_cbranch_execnz .LBB0_179

.LBB0_179:
	s_waitcnt vmcnt(0)
	v_mul_f32_e32 v35, v38, v41
	ds_write2_b32 v39, v40, v35 offset0:140 offset1:206
	s_and_b64 vcc, exec, s[40:41]
	v_add_u32_e32 v35, 0x800, v43
	s_cbranch_vccnz .LBB0_188
	v_mov_b32_e32 v36, v124
	v_mov_b32_e32 v37, v125
	s_waitcnt vmcnt(1)
	v_mul_f32_e32 v36, v0, v36
	s_waitcnt vmcnt(0)
	v_mul_f32_e32 v37, v32, v37
	ds_write2_b32 v35, v36, v37 offset0:16 offset1:82
	v_mov_b32_e32 v36, v126
	s_waitcnt vmcnt(0)
	v_mul_f32_e32 v36, v33, v36
	v_mov_b32_e32 v12, v127
	s_cbranch_execnz .LBB0_121
	s_branch .LBB0_189

.LBB0_366:
	s_min_u32 s26, s24, 28
	s_mul_i32 s26, s26, 0x48000
	s_add_i32 s27, s17, s23
	s_add_i32 s58, s26, 0xd8000
	s_waitcnt vmcnt(4)
	s_barrier
	s_add_i32 s26, s22, 0
	v_add_u32_e32 v118, s26, v197
	v_add_u32_e32 v122, s26, v198
	v_add_u32_e32 v126, s26, v199
	ds_read_b128 v[114:117], v118 offset:0
	ds_read_b128 v[182:185], v118 offset:4096
	ds_read_b128 v[118:121], v122 offset:0
	ds_read_b128 v[178:181], v122 offset:4096
	ds_read_b128 v[122:125], v126 offset:0
	ds_read_b128 v[166:169], v126 offset:4096
	v_add_u32_e32 v150, s26, v200
	ds_read_b128 v[126:129], v150 offset:0
	ds_read_b128 v[146:149], v150 offset:4096
	s_add_i32 s25, s25, 0
	v_add_u32_e32 v210, s25, v201
	ds_read_b64_tr_b16 v[162:163], v210 offset:0
	ds_read_b64_tr_b16 v[164:165], v210 offset:2048
	v_add_u32_e32 v211, s25, v206
	ds_read_b64_tr_b16 v[158:159], v211 offset:0
	ds_read_b64_tr_b16 v[160:161], v211 offset:2048
	v_add_u32_e32 v223, s25, v207
	ds_read_b64_tr_b16 v[154:155], v223 offset:0
	ds_read_b64_tr_b16 v[156:157], v223 offset:2048
	v_add_u32_e32 v224, s25, v208
	ds_read_b64_tr_b16 v[150:151], v224 offset:0
	ds_read_b64_tr_b16 v[152:153], v224 offset:2048
	s_waitcnt lgkmcnt(0)
	s_setprio 1
	v_exp_f32_e32 v202, v82
	v_exp_f32_e32 v203, v83
	s_nop 0
	v_cvt_pk_bf16_f32 v170, v202, v203
	v_exp_f32_e32 v204, v84
	v_exp_f32_e32 v205, v85
	s_nop 0
	v_cvt_pk_bf16_f32 v171, v204, v205
	v_exp_f32_e32 v212, v86
	v_exp_f32_e32 v213, v87
	s_nop 0
	v_cvt_pk_bf16_f32 v172, v212, v213
	v_exp_f32_e32 v216, v88
	v_exp_f32_e32 v217, v89
	s_nop 0
	v_cvt_pk_bf16_f32 v173, v216, v217
	v_exp_f32_e32 v218, v90
	v_exp_f32_e32 v219, v91
	v_exp_f32_e32 v226, v92
	v_exp_f32_e32 v227, v93
	v_exp_f32_e32 v228, v94
	v_exp_f32_e32 v229, v95
	v_exp_f32_e32 v230, v96
	v_exp_f32_e32 v225, v97
	v_mfma_f32_32x32x16_bf16 v[82:97], v[114:117], v[130:133], v[2:17]
	v_add_f32_e32 v114, 0, v202
	v_add_f32_e32 v114, v203, v114
	v_add_f32_e32 v114, v204, v114
	v_add_f32_e32 v114, v205, v114
	v_add_f32_e32 v114, v212, v114
	v_add_f32_e32 v114, v213, v114
	v_add_f32_e32 v114, v216, v114
	v_mfma_f32_32x32x16_bf16 v[82:97], v[118:121], v[134:137], v[82:97]
	v_add_f32_e32 v114, v217, v114
	v_add_f32_e32 v114, v218, v114
	v_add_f32_e32 v114, v219, v114
	v_add_f32_e32 v114, v226, v114
	v_add_f32_e32 v114, v227, v114
	v_add_f32_e32 v114, v228, v114
	v_add_f32_e32 v114, v229, v114
	v_mfma_f32_32x32x16_bf16 v[82:97], v[122:125], v[138:141], v[82:97]
	v_add_f32_e32 v202, v230, v114
	v_mfma_f32_32x32x16_bf16 v[82:97], v[126:129], v[142:145], v[82:97]
	v_cvt_pk_bf16_f32 v177, v230, v225
	v_cvt_pk_bf16_f32 v174, v218, v219
	v_cvt_pk_bf16_f32 v175, v226, v227
	v_cvt_pk_bf16_f32 v176, v228, v229
	v_mfma_f32_32x32x16_bf16 v[114:129], v[182:185], v[130:133], v[2:17]
	v_mfma_f32_32x32x16_bf16 v[114:129], v[178:181], v[134:137], v[114:129]
	v_mfma_f32_32x32x16_bf16 v[114:129], v[166:169], v[138:141], v[114:129]
	s_setprio 0
	ds_read_b64_tr_b16 v[166:167], v210 offset:4096
	ds_read_b64_tr_b16 v[168:169], v210 offset:6144
	ds_read_b64_tr_b16 v[178:179], v211 offset:4096
	ds_read_b64_tr_b16 v[180:181], v211 offset:6144
	ds_read_b64_tr_b16 v[182:183], v223 offset:4096
	ds_read_b64_tr_b16 v[184:185], v223 offset:6144
	ds_read_b64_tr_b16 v[226:227], v224 offset:4096
	ds_read_b64_tr_b16 v[228:229], v224 offset:6144
	ds_read_b64_tr_b16 v[230:231], v210 offset:8192
	ds_read_b64_tr_b16 v[232:233], v210 offset:10240
	ds_read_b64_tr_b16 v[234:235], v211 offset:8192
	ds_read_b64_tr_b16 v[236:237], v211 offset:10240
	ds_read_b64_tr_b16 v[238:239], v223 offset:8192
	ds_read_b64_tr_b16 v[240:241], v223 offset:10240
	ds_read_b64_tr_b16 v[242:243], v224 offset:8192
	ds_read_b64_tr_b16 v[244:245], v224 offset:10240
	ds_read_b64_tr_b16 v[246:247], v210 offset:12288
	ds_read_b64_tr_b16 v[248:249], v210 offset:14336
	v_add_f32_e32 v225, v225, v202
	ds_read_b64_tr_b16 v[202:203], v211 offset:12288
	ds_read_b64_tr_b16 v[204:205], v211 offset:14336
	ds_read_b64_tr_b16 v[210:211], v223 offset:12288
	ds_read_b64_tr_b16 v[212:213], v223 offset:14336
	ds_read_b64_tr_b16 v[216:217], v224 offset:12288
	ds_read_b64_tr_b16 v[218:219], v224 offset:14336
	s_waitcnt lgkmcnt(15)
	s_setprio 1
	v_mfma_f32_32x32x16_bf16 v[66:81], v[162:165], v[170:173], v[66:81]
	v_exp_f32_e32 v162, v98
	v_exp_f32_e32 v163, v99
	s_nop 0
	v_cvt_pk_bf16_f32 v98, v162, v163
	v_mfma_f32_32x32x16_bf16 v[50:65], v[158:161], v[170:173], v[50:65]
	v_exp_f32_e32 v158, v100
	v_exp_f32_e32 v159, v101
	s_nop 0
	v_cvt_pk_bf16_f32 v99, v158, v159
	v_mfma_f32_32x32x16_bf16 v[34:49], v[154:157], v[170:173], v[34:49]
	v_exp_f32_e32 v154, v102
	v_exp_f32_e32 v155, v103
	s_nop 0
	v_cvt_pk_bf16_f32 v100, v154, v155
	v_mfma_f32_32x32x16_bf16 v[18:33], v[150:153], v[170:173], v[18:33]
	v_exp_f32_e32 v150, v104
	v_exp_f32_e32 v151, v105
	v_add_f32_e32 v152, v162, v225
	v_add_f32_e32 v152, v163, v152
	v_add_f32_e32 v152, v158, v152
	v_cvt_pk_bf16_f32 v101, v150, v151
	v_add_f32_e32 v152, v159, v152
	v_mfma_f32_32x32x16_bf16 v[66:81], v[166:169], v[174:177], v[66:81]
	v_exp_f32_e32 v106, v106
	v_exp_f32_e32 v107, v107
	v_add_f32_e32 v152, v154, v152
	v_add_f32_e32 v152, v155, v152
	v_add_f32_e32 v150, v150, v152
	v_cvt_pk_bf16_f32 v102, v106, v107
	v_add_f32_e32 v150, v151, v150
	v_mfma_f32_32x32x16_bf16 v[50:65], v[178:181], v[174:177], v[50:65]
	v_exp_f32_e32 v108, v108
	v_exp_f32_e32 v109, v109
	v_add_f32_e32 v106, v106, v150
	v_add_f32_e32 v106, v107, v106
	v_add_f32_e32 v106, v108, v106
	v_cvt_pk_bf16_f32 v103, v108, v109
	v_add_f32_e32 v106, v109, v106
	v_mfma_f32_32x32x16_bf16 v[34:49], v[182:185], v[174:177], v[34:49]
	v_exp_f32_e32 v110, v110
	v_exp_f32_e32 v111, v111
	v_add_f32_e32 v106, v110, v106
	v_cvt_pk_bf16_f32 v104, v110, v111
	v_add_f32_e32 v106, v111, v106
	v_mfma_f32_32x32x16_bf16 v[18:33], v[226:229], v[174:177], v[18:33]
	v_exp_f32_e32 v112, v112
	v_exp_f32_e32 v113, v113
	v_add_f32_e32 v106, v112, v106
	v_cvt_pk_bf16_f32 v105, v112, v113
	v_add_f32_e32 v106, v113, v106
	v_mfma_f32_32x32x16_bf16 v[114:129], v[146:149], v[142:145], v[114:129]
	s_waitcnt lgkmcnt(0)
	v_mfma_f32_32x32x16_bf16 v[66:81], v[230:233], v[98:101], v[66:81]
	v_add_f32_e32 v209, v209, v106
	v_mfma_f32_32x32x16_bf16 v[50:65], v[234:237], v[98:101], v[50:65]
	v_lshl_add_u64 v[108:109], v[186:187], 0, s[58:59]
	s_mov_b32 m0, s27
	s_nop 0
	global_load_lds_dwordx4 v[108:109], off
	v_mfma_f32_32x32x16_bf16 v[34:49], v[238:241], v[98:101], v[34:49]
	v_mfma_f32_32x32x16_bf16 v[18:33], v[242:245], v[98:101], v[18:33]
	v_lshl_add_u64 v[108:109], v[108:109], 0, s[28:29]
	s_add_i32 m0, s27, 0x2000
	s_nop 0
	global_load_lds_dwordx4 v[108:109], off
	v_mfma_f32_32x32x16_bf16 v[66:81], v[246:249], v[102:105], v[66:81]
	v_mfma_f32_32x32x16_bf16 v[50:65], v[202:205], v[102:105], v[50:65]
	v_lshl_add_u64 v[108:109], v[188:189], 0, s[58:59]
	s_add_i32 m0, s27, 0x4000
	s_nop 0
	global_load_lds_dwordx4 v[108:109], off
	v_mfma_f32_32x32x16_bf16 v[34:49], v[210:213], v[102:105], v[34:49]
	v_mfma_f32_32x32x16_bf16 v[18:33], v[216:219], v[102:105], v[18:33]
	v_lshl_add_u64 v[108:109], v[108:109], 0, s[34:35]
	s_add_i32 m0, s27, 0x6000
	s_nop 0
	global_load_lds_dwordx4 v[108:109], off
	s_setprio 0
	s_add_i32 s26, s22, 0x8000
	s_cmp_lg_u32 s22, 0x18000
	s_mov_b32 s25, s22
	s_cselect_b32 s22, s26, 0
	s_add_i32 s26, s23, 0x8000
	s_cmp_lg_u32 s23, 0x18000
	v_mov_b64_e32 v[98:99], v[114:115]
	s_cselect_b32 s23, s26, 0
	s_add_i32 s24, s24, 1
	v_mov_b64_e32 v[100:101], v[116:117]
	v_mov_b64_e32 v[102:103], v[118:119]
	v_mov_b64_e32 v[104:105], v[120:121]
	v_mov_b64_e32 v[106:107], v[122:123]
	v_mov_b64_e32 v[108:109], v[124:125]
	v_mov_b64_e32 v[110:111], v[126:127]
	v_mov_b64_e32 v[112:113], v[128:129]
	s_cmp_eq_u32 s24, 32
	s_cbranch_scc0 .LBB0_366
	global_load_dwordx4 v[98:101], v0, s[10:11]
	global_load_dwordx4 v[102:105], v0, s[10:11] offset:32
	global_load_dwordx4 v[106:109], v0, s[10:11] offset:64
	global_load_dwordx4 v[110:113], v0, s[10:11] offset:96
	global_load_dwordx4 v[114:117], v0, s[10:11] offset:128
	global_load_dwordx4 v[118:121], v0, s[10:11] offset:160
	global_load_dwordx4 v[122:125], v0, s[10:11] offset:192
	global_load_dwordx4 v[126:129], v0, s[10:11] offset:224
	global_load_dwordx4 v[130:133], v0, s[10:11] offset:256
	global_load_dwordx4 v[134:137], v0, s[10:11] offset:288
	global_load_dwordx4 v[138:141], v0, s[10:11] offset:320
	global_load_dwordx4 v[142:145], v0, s[10:11] offset:352
	global_load_dwordx4 v[146:149], v0, s[10:11] offset:384
	global_load_dwordx4 v[150:153], v0, s[10:11] offset:416
	global_load_dwordx4 v[154:157], v0, s[10:11] offset:448
	global_load_dwordx4 v[158:161], v0, s[10:11] offset:480
	ds_bpermute_b32 v82, v221, v209
	s_lshl_b32 s17, s21, 14
	s_add_i32 s17, s17, 0
	s_waitcnt vmcnt(0)
	s_cmp_eq_u32 s16, 0
	s_waitcnt lgkmcnt(0)
	v_add_f32_e32 v82, v209, v82
	v_div_scale_f32 v83, s[22:23], v82, v82, 1.0
	v_rcp_f32_e32 v84, v83
	v_div_scale_f32 v85, vcc, 1.0, v82, 1.0
	v_lshl_add_u32 v92, v196, 4, s17
	v_fma_f32 v86, -v83, v84, 1.0
	v_fmac_f32_e32 v84, v86, v84
	v_mul_f32_e32 v86, v85, v84
	v_fma_f32 v87, -v83, v86, v85
	v_fmac_f32_e32 v86, v87, v84
	v_fma_f32 v83, -v83, v86, v85
	v_div_fmas_f32 v83, v83, v84, v86
	s_cselect_b64 s[16:17], -1, 0
	v_div_fixup_f32 v82, v83, v82, 1.0
	s_and_b64 vcc, exec, s[16:17]
	s_waitcnt vmcnt(0)
	s_barrier
	s_cbranch_vccnz .LBB0_369
	v_pk_mul_f32 v[86:87], v[68:69], v[82:83] op_sel_hi:[1,0]
	v_pk_mul_f32 v[84:85], v[66:67], v[82:83] op_sel_hi:[1,0]
	ds_write_b128 v92, v[84:87]
	v_pk_mul_f32 v[86:87], v[72:73], v[82:83] op_sel_hi:[1,0]
	v_pk_mul_f32 v[84:85], v[70:71], v[82:83] op_sel_hi:[1,0]
	ds_write_b128 v92, v[84:87] offset:1024
	v_pk_mul_f32 v[86:87], v[76:77], v[82:83] op_sel_hi:[1,0]
	v_pk_mul_f32 v[84:85], v[74:75], v[82:83] op_sel_hi:[1,0]
	ds_write_b128 v92, v[84:87] offset:2048
	v_pk_mul_f32 v[86:87], v[80:81], v[82:83] op_sel_hi:[1,0]
	v_pk_mul_f32 v[84:85], v[78:79], v[82:83] op_sel_hi:[1,0]
	ds_write_b128 v92, v[84:87] offset:3072
	v_pk_mul_f32 v[86:87], v[52:53], v[82:83] op_sel_hi:[1,0]
	v_pk_mul_f32 v[84:85], v[50:51], v[82:83] op_sel_hi:[1,0]
	ds_write_b128 v92, v[84:87] offset:4096
	v_pk_mul_f32 v[86:87], v[56:57], v[82:83] op_sel_hi:[1,0]
	v_pk_mul_f32 v[84:85], v[54:55], v[82:83] op_sel_hi:[1,0]
	ds_write_b128 v92, v[84:87] offset:5120
	v_pk_mul_f32 v[86:87], v[60:61], v[82:83] op_sel_hi:[1,0]
	v_pk_mul_f32 v[84:85], v[58:59], v[82:83] op_sel_hi:[1,0]
	ds_write_b128 v92, v[84:87] offset:6144
	v_pk_mul_f32 v[86:87], v[64:65], v[82:83] op_sel_hi:[1,0]
	v_pk_mul_f32 v[84:85], v[62:63], v[82:83] op_sel_hi:[1,0]
	ds_write_b128 v92, v[84:87] offset:7168
	v_pk_mul_f32 v[86:87], v[36:37], v[82:83] op_sel_hi:[1,0]
	v_pk_mul_f32 v[84:85], v[34:35], v[82:83] op_sel_hi:[1,0]
	ds_write_b128 v92, v[84:87] offset:8192
	v_pk_mul_f32 v[86:87], v[40:41], v[82:83] op_sel_hi:[1,0]
	v_pk_mul_f32 v[84:85], v[38:39], v[82:83] op_sel_hi:[1,0]
	ds_write_b128 v92, v[84:87] offset:9216
	v_pk_mul_f32 v[86:87], v[44:45], v[82:83] op_sel_hi:[1,0]
	v_pk_mul_f32 v[84:85], v[42:43], v[82:83] op_sel_hi:[1,0]
	ds_write_b128 v92, v[84:87] offset:10240
	v_pk_mul_f32 v[86:87], v[48:49], v[82:83] op_sel_hi:[1,0]
	v_pk_mul_f32 v[84:85], v[46:47], v[82:83] op_sel_hi:[1,0]
	ds_write_b128 v92, v[84:87] offset:11264
	v_pk_mul_f32 v[86:87], v[20:21], v[82:83] op_sel_hi:[1,0]
	v_pk_mul_f32 v[84:85], v[18:19], v[82:83] op_sel_hi:[1,0]
	ds_write_b128 v92, v[84:87] offset:12288
	v_pk_mul_f32 v[86:87], v[24:25], v[82:83] op_sel_hi:[1,0]
	v_pk_mul_f32 v[84:85], v[22:23], v[82:83] op_sel_hi:[1,0]
	ds_write_b128 v92, v[84:87] offset:13312
	v_pk_mul_f32 v[86:87], v[28:29], v[82:83] op_sel_hi:[1,0]
	v_pk_mul_f32 v[84:85], v[26:27], v[82:83] op_sel_hi:[1,0]
	ds_write_b128 v92, v[84:87] offset:14336
	v_pk_mul_f32 v[86:87], v[32:33], v[82:83] op_sel_hi:[1,0]
	v_pk_mul_f32 v[84:85], v[30:31], v[82:83] op_sel_hi:[1,0]
	ds_write_b128 v92, v[84:87] offset:15360
.LBB0_369:
	s_andn2_b64 vcc, exec, s[16:17]
	v_mov_b64_e32 v[248:249], v[250:251]
	s_waitcnt lgkmcnt(0)
	s_barrier
	s_cbranch_vccnz .LBB0_364
	ds_read_b128 v[84:87], v92
	v_mov_b32_e32 v83, s6
	v_mov_b32_e32 v88, v66
	ds_read_b128 v[94:97], v92 offset:5120
	s_mulk_i32 s21, 0x2200
	s_waitcnt lgkmcnt(1)
	v_mov_b32_e32 v89, v84
	v_mov_b32_e32 v84, v67
	v_pk_mul_f32 v[84:85], v[84:85], v[82:83]
	v_pk_mul_f32 v[88:89], v[88:89], v[82:83]
	v_sub_f32_e32 v67, v84, v85
	v_mov_b32_e32 v84, v68
	v_mov_b32_e32 v85, v86
	v_pk_mul_f32 v[84:85], v[84:85], v[82:83]
	v_mov_b32_e32 v86, v69
	v_sub_f32_e32 v68, v84, v85
	v_pk_mul_f32 v[84:85], v[86:87], v[82:83]
	v_sub_f32_e32 v66, v88, v89
	v_sub_f32_e32 v69, v84, v85
	ds_read_b128 v[84:87], v92 offset:1024
	v_mov_b32_e32 v88, v70
	s_add_i32 s16, s21, 0
	s_add_i32 s16, s16, 0x10000
	s_lshl_b64 s[14:15], s[14:15], 11
	s_waitcnt lgkmcnt(0)
	v_mov_b32_e32 v89, v84
	v_mov_b32_e32 v84, v71
	v_pk_mul_f32 v[84:85], v[84:85], v[82:83]
	v_pk_mul_f32 v[88:89], v[88:89], v[82:83]
	v_sub_f32_e32 v71, v84, v85
	v_mov_b32_e32 v84, v72
	v_mov_b32_e32 v85, v86
	v_pk_mul_f32 v[84:85], v[84:85], v[82:83]
	v_mov_b32_e32 v86, v73
	v_sub_f32_e32 v72, v84, v85
	v_pk_mul_f32 v[84:85], v[86:87], v[82:83]
	v_sub_f32_e32 v70, v88, v89
	v_sub_f32_e32 v73, v84, v85
	ds_read_b128 v[84:87], v92 offset:2048
	v_mov_b32_e32 v88, v74
	s_add_u32 s14, s18, s14
	s_addc_u32 s15, s19, s15
	s_lshl_b32 s17, s20, 1
	s_waitcnt lgkmcnt(0)
	v_mov_b32_e32 v89, v84
	v_mov_b32_e32 v84, v75
	v_pk_mul_f32 v[84:85], v[84:85], v[82:83]
	v_pk_mul_f32 v[88:89], v[88:89], v[82:83]
	v_sub_f32_e32 v75, v84, v85
	v_mov_b32_e32 v84, v76
	v_mov_b32_e32 v85, v86
	v_pk_mul_f32 v[84:85], v[84:85], v[82:83]
	v_mov_b32_e32 v86, v77
	v_sub_f32_e32 v76, v84, v85
	v_pk_mul_f32 v[84:85], v[86:87], v[82:83]
	v_sub_f32_e32 v74, v88, v89
	v_sub_f32_e32 v77, v84, v85
	ds_read_b128 v[84:87], v92 offset:3072
	v_mov_b32_e32 v88, v78
	s_add_u32 s14, s14, s17
	s_addc_u32 s15, s15, 0
	s_waitcnt lgkmcnt(0)
	v_mov_b32_e32 v89, v84
	v_mov_b32_e32 v84, v79
	v_pk_mul_f32 v[84:85], v[84:85], v[82:83]
	v_pk_mul_f32 v[88:89], v[88:89], v[82:83]
	v_sub_f32_e32 v79, v84, v85
	v_mov_b32_e32 v84, v80
	v_mov_b32_e32 v85, v86
	v_pk_mul_f32 v[84:85], v[84:85], v[82:83]
	v_mov_b32_e32 v86, v81
	v_sub_f32_e32 v78, v88, v89
	v_sub_f32_e32 v80, v84, v85
	v_pk_mul_f32 v[84:85], v[86:87], v[82:83]
	ds_read_b128 v[86:89], v92 offset:4096
	v_sub_f32_e32 v81, v84, v85
	v_mov_b32_e32 v84, v50
	s_waitcnt lgkmcnt(0)
	v_mov_b32_e32 v85, v86
	v_mov_b32_e32 v86, v51
	v_pk_mul_f32 v[84:85], v[84:85], v[82:83]
	v_pk_mul_f32 v[50:51], v[86:87], v[82:83]
	v_sub_f32_e32 v85, v84, v85
	v_sub_f32_e32 v84, v50, v51
	v_mov_b32_e32 v50, v52
	v_mov_b32_e32 v51, v88
	v_mov_b32_e32 v88, v53
	v_pk_mul_f32 v[50:51], v[50:51], v[82:83]
	v_pk_mul_f32 v[52:53], v[88:89], v[82:83]
	v_sub_f32_e32 v51, v50, v51
	v_sub_f32_e32 v50, v52, v53
	v_mov_b32_e32 v52, v54
	v_mov_b32_e32 v53, v94
	v_pk_mul_f32 v[52:53], v[52:53], v[82:83]
	v_mov_b32_e32 v94, v55
	v_sub_f32_e32 v88, v52, v53
	v_pk_mul_f32 v[52:53], v[94:95], v[82:83]
	s_nop 0
	v_sub_f32_e32 v87, v52, v53
	v_mov_b32_e32 v52, v56
	v_mov_b32_e32 v53, v96
	v_pk_mul_f32 v[52:53], v[52:53], v[82:83]
	v_mov_b32_e32 v96, v57
	v_sub_f32_e32 v86, v52, v53
	v_pk_mul_f32 v[52:53], v[96:97], v[82:83]
	ds_read_b128 v[94:97], v92 offset:6144
	v_sub_f32_e32 v56, v52, v53
	v_mov_b32_e32 v52, v58
	s_waitcnt lgkmcnt(0)
	v_mov_b32_e32 v53, v94
	v_pk_mul_f32 v[52:53], v[52:53], v[82:83]
	v_mov_b32_e32 v94, v59
	v_sub_f32_e32 v55, v52, v53
	v_pk_mul_f32 v[52:53], v[94:95], v[82:83]
	s_nop 0
	v_sub_f32_e32 v54, v52, v53
	v_mov_b32_e32 v53, v96
	v_mov_b32_e32 v96, v61
	v_pk_mul_f32 v[58:59], v[96:97], v[82:83]
	ds_read_b128 v[94:97], v92 offset:7168
	v_mov_b32_e32 v52, v60
	v_pk_mul_f32 v[52:53], v[52:53], v[82:83]
	s_nop 0
	v_sub_f32_e32 v53, v52, v53
	v_sub_f32_e32 v52, v58, v59
	v_mov_b32_e32 v58, v62
	s_waitcnt lgkmcnt(0)
	v_mov_b32_e32 v59, v94
	v_pk_mul_f32 v[58:59], v[58:59], v[82:83]
	v_mov_b32_e32 v94, v63
	v_sub_f32_e32 v89, v58, v59
	v_pk_mul_f32 v[58:59], v[94:95], v[82:83]
	s_nop 0
	v_sub_f32_e32 v62, v58, v59
	v_mov_b32_e32 v58, v64
	v_mov_b32_e32 v59, v96
	v_pk_mul_f32 v[58:59], v[58:59], v[82:83]
	v_mov_b32_e32 v96, v65
	v_sub_f32_e32 v61, v58, v59
	v_pk_mul_f32 v[58:59], v[96:97], v[82:83]
	ds_read_b128 v[94:97], v92 offset:8192
	v_sub_f32_e32 v60, v58, v59
	v_mov_b32_e32 v58, v34
	s_waitcnt lgkmcnt(0)
	v_mov_b32_e32 v59, v94
	v_mov_b32_e32 v94, v35
	v_pk_mul_f32 v[58:59], v[58:59], v[82:83]
	v_pk_mul_f32 v[34:35], v[94:95], v[82:83]
	v_sub_f32_e32 v59, v58, v59
	v_sub_f32_e32 v58, v34, v35
	v_mov_b32_e32 v34, v36
	v_mov_b32_e32 v35, v96
	v_pk_mul_f32 v[34:35], v[34:35], v[82:83]
	v_mov_b32_e32 v96, v37
	v_sub_f32_e32 v57, v34, v35
	v_pk_mul_f32 v[34:35], v[96:97], v[82:83]
	ds_read_b128 v[94:97], v92 offset:9216
	v_sub_f32_e32 v36, v34, v35
	v_mov_b32_e32 v34, v38
	s_waitcnt lgkmcnt(0)
	v_mov_b32_e32 v35, v94
	v_pk_mul_f32 v[34:35], v[34:35], v[82:83]
	v_mov_b32_e32 v94, v39
	v_sub_f32_e32 v65, v34, v35
	v_pk_mul_f32 v[34:35], v[94:95], v[82:83]
	s_nop 0
	v_sub_f32_e32 v64, v34, v35
	v_mov_b32_e32 v34, v40
	v_mov_b32_e32 v35, v96
	v_pk_mul_f32 v[34:35], v[34:35], v[82:83]
	v_mov_b32_e32 v96, v41
	v_sub_f32_e32 v63, v34, v35
	v_pk_mul_f32 v[34:35], v[96:97], v[82:83]
	ds_read_b128 v[94:97], v92 offset:10240
	v_sub_f32_e32 v41, v34, v35
	v_mov_b32_e32 v34, v42
	s_waitcnt lgkmcnt(0)
	v_mov_b32_e32 v35, v94
	v_pk_mul_f32 v[34:35], v[34:35], v[82:83]
	v_mov_b32_e32 v94, v43
	v_sub_f32_e32 v40, v34, v35
	v_pk_mul_f32 v[34:35], v[94:95], v[82:83]
	s_nop 0
	v_sub_f32_e32 v39, v34, v35
	v_mov_b32_e32 v34, v44
	v_mov_b32_e32 v35, v96
	v_mov_b32_e32 v96, v45
	ds_read_b128 v[42:45], v92 offset:11264
	v_pk_mul_f32 v[34:35], v[34:35], v[82:83]
	s_nop 0
	v_sub_f32_e32 v38, v34, v35
	v_pk_mul_f32 v[34:35], v[96:97], v[82:83]
	ds_read_b128 v[94:97], v92 offset:12288
	v_sub_f32_e32 v37, v34, v35
	v_mov_b32_e32 v34, v46
	s_waitcnt lgkmcnt(1)
	v_mov_b32_e32 v35, v42
	v_pk_mul_f32 v[34:35], v[34:35], v[82:83]
	v_mov_b32_e32 v42, v47
	v_sub_f32_e32 v91, v34, v35
	v_pk_mul_f32 v[34:35], v[42:43], v[82:83]
	s_nop 0
	v_sub_f32_e32 v90, v34, v35
	v_mov_b32_e32 v34, v48
	v_mov_b32_e32 v35, v44
	v_pk_mul_f32 v[34:35], v[34:35], v[82:83]
	v_mov_b32_e32 v44, v49
	v_sub_f32_e32 v47, v34, v35
	v_pk_mul_f32 v[34:35], v[44:45], v[82:83]
	s_nop 0
	v_sub_f32_e32 v46, v34, v35
	s_waitcnt lgkmcnt(0)
	v_mov_b32_e32 v35, v94
	v_mov_b32_e32 v94, v19
	v_mov_b32_e32 v34, v18
	v_pk_mul_f32 v[18:19], v[94:95], v[82:83]
	v_pk_mul_f32 v[34:35], v[34:35], v[82:83]
	v_sub_f32_e32 v44, v18, v19
	v_mov_b32_e32 v18, v20
	v_mov_b32_e32 v19, v96
	v_pk_mul_f32 v[18:19], v[18:19], v[82:83]
	v_mov_b32_e32 v96, v21
	v_sub_f32_e32 v43, v18, v19
	v_pk_mul_f32 v[18:19], v[96:97], v[82:83]
	v_sub_f32_e32 v45, v34, v35
	v_sub_f32_e32 v42, v18, v19
	ds_read_b128 v[18:21], v92 offset:13312
	v_mov_b32_e32 v34, v22
	s_waitcnt lgkmcnt(0)
	v_mov_b32_e32 v35, v18
	v_mov_b32_e32 v18, v23
	v_pk_mul_f32 v[18:19], v[18:19], v[82:83]
	v_pk_mul_f32 v[34:35], v[34:35], v[82:83]
	v_sub_f32_e32 v48, v18, v19
	v_mov_b32_e32 v18, v24
	v_mov_b32_e32 v19, v20
	v_mov_b32_e32 v20, v25
	v_pk_mul_f32 v[18:19], v[18:19], v[82:83]
	v_pk_mul_f32 v[20:21], v[20:21], v[82:83]
	v_mov_b32_e32 v23, v18
	v_mov_b32_e32 v22, v20
	v_mov_b32_e32 v18, v21
	v_sub_f32_e32 v49, v34, v35
	v_pk_add_f32 v[34:35], v[22:23], v[18:19] neg_lo:[0,1] neg_hi:[0,1]
	ds_read_b128 v[20:23], v92 offset:14336
	v_mov_b32_e32 v24, v26
	v_pk_mul_f32 v[18:19], v[34:35], v[34:35]
	s_waitcnt lgkmcnt(0)
	v_mov_b32_e32 v25, v20
	v_mov_b32_e32 v20, v27
	v_pk_mul_f32 v[24:25], v[24:25], v[82:83]
	v_pk_mul_f32 v[20:21], v[20:21], v[82:83]
	v_mov_b32_e32 v27, v24
	v_mov_b32_e32 v26, v20
	v_mov_b32_e32 v24, v21
	v_pk_add_f32 v[24:25], v[26:27], v[24:25] neg_lo:[0,1] neg_hi:[0,1]
	v_mov_b32_e32 v26, v28
	v_mov_b32_e32 v27, v22
	v_mov_b32_e32 v22, v29
	v_pk_mul_f32 v[26:27], v[26:27], v[82:83]
	v_pk_mul_f32 v[22:23], v[22:23], v[82:83]
	v_mov_b32_e32 v29, v26
	v_mov_b32_e32 v28, v22
	v_mov_b32_e32 v26, v23
	v_pk_add_f32 v[22:23], v[28:29], v[26:27] neg_lo:[0,1] neg_hi:[0,1]
	ds_read_b128 v[26:29], v92 offset:15360
	v_mov_b32_e32 v92, v30
	v_pk_mul_f32 v[20:21], v[24:25], v[24:25]
	v_pk_mul_f32 v[94:95], v[22:23], v[22:23]
	s_waitcnt lgkmcnt(0)
	v_mov_b32_e32 v93, v26
	v_mov_b32_e32 v26, v31
	v_pk_mul_f32 v[28:29], s[6:7], v[28:29]
	v_pk_mul_f32 v[92:93], v[92:93], v[82:83]
	v_pk_mul_f32 v[26:27], v[26:27], v[82:83]
	v_pk_fma_f32 v[28:29], v[32:33], v[82:83], v[28:29] op_sel_hi:[1,0,1] neg_lo:[0,0,1] neg_hi:[0,0,1]
	v_mul_f32_e32 v82, v66, v66
	v_fmac_f32_e32 v82, v67, v67
	v_fmac_f32_e32 v82, v68, v68
	v_fmac_f32_e32 v82, v69, v69
	v_fmac_f32_e32 v82, v70, v70
	v_fmac_f32_e32 v82, v71, v71
	v_fmac_f32_e32 v82, v72, v72
	v_fmac_f32_e32 v82, v73, v73
	v_fmac_f32_e32 v82, v74, v74
	v_fmac_f32_e32 v82, v75, v75
	v_fmac_f32_e32 v82, v76, v76
	v_fmac_f32_e32 v82, v77, v77
	v_fmac_f32_e32 v82, v78, v78
	v_fmac_f32_e32 v82, v79, v79
	v_fmac_f32_e32 v82, v80, v80
	v_fmac_f32_e32 v82, v81, v81
	v_fmac_f32_e32 v82, v85, v85
	v_fmac_f32_e32 v82, v84, v84
	v_fmac_f32_e32 v82, v51, v51
	v_fmac_f32_e32 v82, v50, v50
	v_fmac_f32_e32 v82, v88, v88
	v_fmac_f32_e32 v82, v87, v87
	v_fmac_f32_e32 v82, v86, v86
	v_fmac_f32_e32 v82, v56, v56
	v_fmac_f32_e32 v82, v55, v55
	v_fmac_f32_e32 v82, v54, v54
	v_fmac_f32_e32 v82, v53, v53
	v_fmac_f32_e32 v82, v52, v52
	v_fmac_f32_e32 v82, v89, v89
	v_fmac_f32_e32 v82, v62, v62
	v_fmac_f32_e32 v82, v61, v61
	v_fmac_f32_e32 v82, v60, v60
	v_fmac_f32_e32 v82, v59, v59
	v_fmac_f32_e32 v82, v58, v58
	v_fmac_f32_e32 v82, v57, v57
	v_fmac_f32_e32 v82, v36, v36
	v_fmac_f32_e32 v82, v65, v65
	v_fmac_f32_e32 v82, v64, v64
	v_fmac_f32_e32 v82, v63, v63
	v_fmac_f32_e32 v82, v41, v41
	v_fmac_f32_e32 v82, v40, v40
	v_fmac_f32_e32 v82, v39, v39
	v_fmac_f32_e32 v82, v38, v38
	v_fmac_f32_e32 v82, v37, v37
	v_fmac_f32_e32 v82, v91, v91
	v_fmac_f32_e32 v82, v90, v90
	v_fmac_f32_e32 v82, v47, v47
	v_fmac_f32_e32 v82, v46, v46
	v_fmac_f32_e32 v82, v45, v45
	v_fmac_f32_e32 v82, v44, v44
	v_fmac_f32_e32 v82, v43, v43
	v_fmac_f32_e32 v82, v42, v42
	v_fmac_f32_e32 v82, v49, v49
	v_fmac_f32_e32 v82, v48, v48
	v_add_f32_e32 v19, v19, v82
	v_add_f32_e32 v18, v18, v19
	v_add_f32_e32 v18, v21, v18
	v_mov_b32_e32 v30, v26
	v_mov_b32_e32 v31, v92
	v_mov_b32_e32 v92, v27
	v_add_f32_e32 v18, v20, v18
	v_pk_add_f32 v[26:27], v[30:31], v[92:93] neg_lo:[0,1] neg_hi:[0,1]
	v_add_f32_e32 v18, v95, v18
	v_pk_mul_f32 v[30:31], v[26:27], v[26:27]
	v_add_f32_e32 v18, v94, v18
	v_add_f32_e32 v18, v31, v18
	v_pk_mul_f32 v[32:33], v[28:29], v[28:29]
	v_add_f32_e32 v18, v30, v18
	v_add_f32_e32 v18, v32, v18
	v_add_f32_e32 v18, v33, v18
	ds_bpermute_b32 v19, v221, v18
	v_mul_u32_u24_e32 v31, 0x110, v195
	s_waitcnt lgkmcnt(0)
	v_add_f32_e32 v18, v18, v19
	v_fmamk_f32 v18, v18, 0x3c000000, v214
	v_cmp_gt_f32_e32 vcc, s90, v18
	v_mul_f32_e32 v19, 0x4b800000, v18
	s_nop 0
	v_cndmask_b32_e32 v18, v18, v19, vcc
	v_rsq_f32_e32 v18, v18
	s_nop 0
	v_mul_f32_e32 v19, 0x45800000, v18
	v_cndmask_b32_e32 v18, v18, v19, vcc
	v_mul_f32_e32 v30, v190, v18
	v_mul_f32_e32 v32, v66, v30
	s_waitcnt vmcnt(0)
	v_mul_f32_e32 v18, v98, v32
	v_mul_f32_e32 v32, v67, v30
	v_mul_f32_e32 v19, v99, v32
	v_cvt_pk_bf16_f32 v32, v18, v19
	v_mul_f32_e32 v18, v68, v30
	v_mul_f32_e32 v19, v69, v30
	v_mul_f32_e32 v18, v100, v18
	v_mul_f32_e32 v19, v101, v19
	v_cvt_pk_bf16_f32 v33, v18, v19
	v_mul_f32_e32 v19, v70, v30
	v_mul_f32_e32 v20, v71, v30
	v_add3_u32 v18, s16, v31, v194
	v_mul_f32_e32 v21, v73, v30
	ds_write_b64 v18, v[32:33]
	v_mul_f32_e32 v19, v102, v19
	v_mul_f32_e32 v20, v103, v20
	v_cvt_pk_bf16_f32 v20, v19, v20
	v_mul_f32_e32 v19, v72, v30
	v_mul_f32_e32 v21, v105, v21
	v_mul_f32_e32 v19, v104, v19
	v_cvt_pk_bf16_f32 v21, v19, v21
	ds_write_b64 v18, v[20:21] offset:16
	v_mul_f32_e32 v19, v74, v30
	v_mul_f32_e32 v20, v75, v30
	v_mul_f32_e32 v21, v77, v30
	v_mul_f32_e32 v19, v106, v19
	v_mul_f32_e32 v20, v107, v20
	v_cvt_pk_bf16_f32 v20, v19, v20
	v_mul_f32_e32 v19, v76, v30
	v_mul_f32_e32 v21, v109, v21
	v_mul_f32_e32 v19, v108, v19
	v_cvt_pk_bf16_f32 v21, v19, v21
	ds_write_b64 v18, v[20:21] offset:32
	v_mul_f32_e32 v19, v78, v30
	v_mul_f32_e32 v20, v79, v30
	v_mul_f32_e32 v21, v81, v30
	v_mul_f32_e32 v19, v110, v19
	v_mul_f32_e32 v20, v111, v20
	v_cvt_pk_bf16_f32 v20, v19, v20
	v_mul_f32_e32 v19, v80, v30
	v_mul_f32_e32 v21, v113, v21
	v_mul_f32_e32 v19, v112, v19
	v_cvt_pk_bf16_f32 v21, v19, v21
	ds_write_b64 v18, v[20:21] offset:48
	v_mul_f32_e32 v19, v85, v30
	v_mul_f32_e32 v20, v84, v30
	v_mul_f32_e32 v21, v50, v30
	v_mul_f32_e32 v19, v114, v19
	v_mul_f32_e32 v20, v115, v20
	v_cvt_pk_bf16_f32 v20, v19, v20
	v_mul_f32_e32 v19, v51, v30
	v_mul_f32_e32 v21, v117, v21
	v_mul_f32_e32 v19, v116, v19
	v_cvt_pk_bf16_f32 v21, v19, v21
	ds_write_b64 v18, v[20:21] offset:64
	v_mul_f32_e32 v19, v88, v30
	v_mul_f32_e32 v20, v87, v30
	v_mul_f32_e32 v21, v56, v30
	v_mul_f32_e32 v19, v118, v19
	v_mul_f32_e32 v20, v119, v20
	v_cvt_pk_bf16_f32 v20, v19, v20
	v_mul_f32_e32 v19, v86, v30
	v_mul_f32_e32 v21, v121, v21
	v_mul_f32_e32 v19, v120, v19
	v_cvt_pk_bf16_f32 v21, v19, v21
	ds_write_b64 v18, v[20:21] offset:80
	v_mul_f32_e32 v19, v55, v30
	v_mul_f32_e32 v20, v54, v30
	v_mul_f32_e32 v21, v52, v30
	v_mul_f32_e32 v19, v122, v19
	v_mul_f32_e32 v20, v123, v20
	v_cvt_pk_bf16_f32 v20, v19, v20
	v_mul_f32_e32 v19, v53, v30
	v_mul_f32_e32 v21, v125, v21
	v_mul_f32_e32 v19, v124, v19
	v_cvt_pk_bf16_f32 v21, v19, v21
	ds_write_b64 v18, v[20:21] offset:96
	v_mul_f32_e32 v19, v89, v30
	v_mul_f32_e32 v20, v62, v30
	v_mul_f32_e32 v21, v60, v30
	v_mul_f32_e32 v19, v126, v19
	v_mul_f32_e32 v20, v127, v20
	v_cvt_pk_bf16_f32 v20, v19, v20
	v_mul_f32_e32 v19, v61, v30
	v_mul_f32_e32 v21, v129, v21
	v_mul_f32_e32 v19, v128, v19
	v_cvt_pk_bf16_f32 v21, v19, v21
	ds_write_b64 v18, v[20:21] offset:112
	v_mul_f32_e32 v19, v59, v30
	v_mul_f32_e32 v20, v58, v30
	v_mul_f32_e32 v21, v36, v30
	v_mul_f32_e32 v19, v130, v19
	v_mul_f32_e32 v20, v131, v20
	v_cvt_pk_bf16_f32 v20, v19, v20
	v_mul_f32_e32 v19, v57, v30
	v_mul_f32_e32 v21, v133, v21
	v_mul_f32_e32 v19, v132, v19
	v_cvt_pk_bf16_f32 v21, v19, v21
	ds_write_b64 v18, v[20:21] offset:128
	v_mul_f32_e32 v19, v65, v30
	v_mul_f32_e32 v20, v64, v30
	v_mul_f32_e32 v21, v41, v30
	v_mul_f32_e32 v19, v134, v19
	v_mul_f32_e32 v20, v135, v20
	v_cvt_pk_bf16_f32 v20, v19, v20
	v_mul_f32_e32 v19, v63, v30
	v_mul_f32_e32 v21, v137, v21
	v_mul_f32_e32 v19, v136, v19
	v_cvt_pk_bf16_f32 v21, v19, v21
	ds_write_b64 v18, v[20:21] offset:144
	v_mul_f32_e32 v19, v40, v30
	v_mul_f32_e32 v20, v39, v30
	v_mul_f32_e32 v21, v37, v30
	v_mul_f32_e32 v19, v138, v19
	v_mul_f32_e32 v20, v139, v20
	v_cvt_pk_bf16_f32 v20, v19, v20
	v_mul_f32_e32 v19, v38, v30
	v_mul_f32_e32 v21, v141, v21
	v_mul_f32_e32 v19, v140, v19
	v_cvt_pk_bf16_f32 v21, v19, v21
	ds_write_b64 v18, v[20:21] offset:160
	v_mul_f32_e32 v19, v91, v30
	v_mul_f32_e32 v20, v90, v30
	v_mul_f32_e32 v21, v46, v30
	v_mul_f32_e32 v19, v142, v19
	v_mul_f32_e32 v20, v143, v20
	v_cvt_pk_bf16_f32 v20, v19, v20
	v_mul_f32_e32 v19, v47, v30
	v_mul_f32_e32 v21, v145, v21
	v_mul_f32_e32 v19, v144, v19
	v_cvt_pk_bf16_f32 v21, v19, v21
	ds_write_b64 v18, v[20:21] offset:176
	v_mul_f32_e32 v19, v45, v30
	v_mul_f32_e32 v20, v44, v30
	v_mul_f32_e32 v21, v42, v30
	v_mul_f32_e32 v19, v146, v19
	v_mul_f32_e32 v20, v147, v20
	v_cvt_pk_bf16_f32 v20, v19, v20
	v_mul_f32_e32 v19, v43, v30
	v_mul_f32_e32 v21, v149, v21
	v_mul_f32_e32 v19, v148, v19
	v_cvt_pk_bf16_f32 v21, v19, v21
	ds_write_b64 v18, v[20:21] offset:192
	v_mul_f32_e32 v19, v49, v30
	v_mul_f32_e32 v20, v48, v30
	v_mul_f32_e32 v21, v34, v30
	v_mul_f32_e32 v19, v150, v19
	v_mul_f32_e32 v20, v151, v20
	v_cvt_pk_bf16_f32 v20, v19, v20
	v_mul_f32_e32 v19, v35, v30
	v_mul_f32_e32 v21, v153, v21
	v_mul_f32_e32 v19, v152, v19
	v_cvt_pk_bf16_f32 v21, v19, v21
	ds_write_b64 v18, v[20:21] offset:208
	v_mul_f32_e32 v19, v25, v30
	v_mul_f32_e32 v20, v24, v30
	v_mul_f32_e32 v21, v22, v30
	v_mul_f32_e32 v19, v154, v19
	v_mul_f32_e32 v20, v155, v20
	v_cvt_pk_bf16_f32 v20, v19, v20
	v_mul_f32_e32 v19, v23, v30
	v_mul_f32_e32 v21, v157, v21
	v_mul_f32_e32 v19, v156, v19
	v_cvt_pk_bf16_f32 v21, v19, v21
	ds_write_b64 v18, v[20:21] offset:224
	v_mul_f32_e32 v0, v27, v30
	v_mul_f32_e32 v19, v26, v30
	v_mul_f32_e32 v0, v158, v0
	v_mul_f32_e32 v19, v159, v19
	v_cvt_pk_bf16_f32 v20, v0, v19
	v_mul_f32_e32 v0, v28, v30
	v_mul_f32_e32 v0, v160, v0
	v_mul_f32_e32 v19, v29, v30
	v_mul_f32_e32 v19, v161, v19
	v_cvt_pk_bf16_f32 v21, v0, v19
	v_lshlrev_b32_e32 v0, 1, v193
	ds_write_b64 v18, v[20:21] offset:240
	v_lshlrev_b32_e32 v20, 4, v192
	v_lshl_add_u64 v[18:19], s[14:15], 0, v[0:1]
	v_mul_u32_u24_e32 v0, 0x110, v191
	s_waitcnt lgkmcnt(0)
	v_add3_u32 v26, s16, v20, v0
	ds_read_b128 v[20:23], v26
	v_lshlrev_b32_e32 v0, 11, v191
	v_lshl_add_u64 v[24:25], v[18:19], 0, v[0:1]
	s_waitcnt lgkmcnt(0)
	global_store_dwordx4 v[24:25], v[20:23], off offset:1024
	ds_read_b128 v[20:23], v26 offset:1088
	v_or_b32_e32 v24, 0x2000, v0
	v_mov_b32_e32 v25, v1
	v_lshl_add_u64 v[24:25], v[18:19], 0, v[24:25]
	s_waitcnt lgkmcnt(0)
	global_store_dwordx4 v[24:25], v[20:23], off offset:1024
	ds_read_b128 v[20:23], v26 offset:2176
	v_or_b32_e32 v24, 0x4000, v0
	v_mov_b32_e32 v25, v1
	v_lshl_add_u64 v[24:25], v[18:19], 0, v[24:25]
	s_waitcnt lgkmcnt(0)
	global_store_dwordx4 v[24:25], v[20:23], off offset:1024
	ds_read_b128 v[20:23], v26 offset:3264
	v_or_b32_e32 v24, 0x6000, v0
	v_mov_b32_e32 v25, v1
	v_lshl_add_u64 v[24:25], v[18:19], 0, v[24:25]
	s_waitcnt lgkmcnt(0)
	global_store_dwordx4 v[24:25], v[20:23], off offset:1024
	ds_read_b128 v[20:23], v26 offset:4352
	v_or_b32_e32 v24, 0x8000, v0
	v_mov_b32_e32 v25, v1
	v_lshl_add_u64 v[24:25], v[18:19], 0, v[24:25]
	s_waitcnt lgkmcnt(0)
	global_store_dwordx4 v[24:25], v[20:23], off offset:1024
	ds_read_b128 v[20:23], v26 offset:5440
	v_or_b32_e32 v24, 0xa000, v0
	v_mov_b32_e32 v25, v1
	v_lshl_add_u64 v[24:25], v[18:19], 0, v[24:25]
	s_waitcnt lgkmcnt(0)
	global_store_dwordx4 v[24:25], v[20:23], off offset:1024
	ds_read_b128 v[20:23], v26 offset:6528
	v_or_b32_e32 v24, 0xc000, v0
	v_mov_b32_e32 v25, v1
	v_lshl_add_u64 v[24:25], v[18:19], 0, v[24:25]
	v_or_b32_e32 v0, 0xe000, v0
	s_waitcnt lgkmcnt(0)
	global_store_dwordx4 v[24:25], v[20:23], off offset:1024
	ds_read_b128 v[20:23], v26 offset:7616
	v_lshl_add_u64 v[18:19], v[18:19], 0, v[0:1]
	s_waitcnt lgkmcnt(0)
	global_store_dwordx4 v[18:19], v[20:23], off offset:1024
	s_branch .LBB0_364

.LBB0_792:
	s_and_saveexec_b64 s[8:9], s[42:43]
	s_cbranch_execz .LBB0_783
	v_readlane_b32 s25, v255, 25
	s_and_b32 s20, s25, 7
	s_cmp_eq_u32 s20, 0
	s_mul_i32 s24, s25, 0x5800
	s_cselect_b64 s[38:39], -1, 0
	s_add_i32 s16, s25, -1
	s_add_i32 s17, s24, 0xffffa800
	s_mul_hi_i32 s16, s16, 0x5800
	s_add_u32 s17, s33, s17
	s_addc_u32 s18, s46, s16
	s_add_u32 s16, s17, 0x2c00
	s_addc_u32 s17, s18, 0
	s_lshl_b32 s26, s25, 8
	s_mul_i32 s18, s25, 0x160000
	s_mul_hi_i32 s19, s26, 0x1600
	s_add_u32 s18, s12, s18
	s_addc_u32 s19, s13, s19
	s_mul_i32 s14, s25, 0x1600
	s_cmp_eq_u32 s20, 7
	s_mul_hi_i32 s15, s25, 0x1600
	s_cselect_b64 s[20:21], -1, 0
	s_add_u32 s22, s14, 0xb00
	s_addc_u32 s23, s15, 0
	s_add_i32 s25, s25, 1
	s_addk_i32 s24, 0x5800
	s_mul_hi_i32 s25, s25, 0x5800
	s_add_u32 s24, s33, s24
	s_addc_u32 s25, s46, s25
	s_or_b32 s26, s26, 0xff
	s_mul_hi_i32 s27, s26, 0x1600
	s_mulk_i32 s26, 0x1600
	s_add_u32 s26, s12, s26
	s_addc_u32 s27, s13, s27
	s_mov_b64 s[30:31], 0
	s_xor_b64 s[38:39], s[38:39], -1
	v_mov_b32_e32 v4, v0
	v_readfirstlane_b32 s40, v0
	v_lshlrev_b32_e32 v2, 2, v0
	v_lshlrev_b32_e32 v3, 1, v0
	v_add_u32_e32 v4, s14, v0
	v_lshlrev_b32_e32 v4, 3, v4
	s_cmp_lt_u32 s40, 0x100
	s_cselect_b64 s[44:45], -1, 0
	s_and_b64 vcc, exec, s[38:39]
	s_cbranch_vccz .Lfx_ldB
	v_add_u32_e32 v21, 0x0, v4
	global_load_dwordx2 v[16:17], v21, s[0:1]
	v_add_u32_e32 v22, 0x0, v2
	global_load_dword v18, v22, s[6:7]
	global_load_dword v19, v22, s[16:17]
	v_add_u32_e32 v20, 0x0, v3
	v_add_u32_e32 v29, 0x1000, v4
	global_load_dwordx2 v[24:25], v29, s[0:1]
	v_add_u32_e32 v30, 0x800, v2
	global_load_dword v26, v30, s[6:7]
	global_load_dword v27, v30, s[16:17]
	v_add_u32_e32 v28, 0x400, v3
	v_add_u32_e32 v37, 0x2000, v4
	global_load_dwordx2 v[32:33], v37, s[0:1]
	v_add_u32_e32 v38, 0x1000, v2
	global_load_dword v34, v38, s[6:7]
	global_load_dword v35, v38, s[16:17]
	v_add_u32_e32 v36, 0x800, v3
	v_add_u32_e32 v45, 0x3000, v4
	global_load_dwordx2 v[40:41], v45, s[0:1]
	v_add_u32_e32 v46, 0x1800, v2
	global_load_dword v42, v46, s[6:7]
	global_load_dword v43, v46, s[16:17]
	v_add_u32_e32 v44, 0xc00, v3
	v_add_u32_e32 v53, 0x4000, v4
	global_load_dwordx2 v[48:49], v53, s[0:1]
	v_add_u32_e32 v54, 0x2000, v2
	global_load_dword v50, v54, s[6:7]
	global_load_dword v51, v54, s[16:17]
	v_add_u32_e32 v52, 0x1000, v3
	s_and_b64 vcc, exec, s[44:45]
	s_cbranch_vccz .Lfx_ldB
	v_add_u32_e32 v61, 0x5000, v4
	global_load_dwordx2 v[56:57], v61, s[0:1]
	v_add_u32_e32 v62, 0x2800, v2
	global_load_dword v58, v62, s[6:7]
	global_load_dword v59, v62, s[16:17]
	v_add_u32_e32 v60, 0x1400, v3
.Lfx_ldB:
	s_andn2_b64 vcc, exec, s[20:21]
	s_cbranch_vccz .Lfx_wait
	v_add_u32_e32 v69, 0x6000, v4
	global_load_dwordx2 v[64:65], v69, s[0:1]
	v_add_u32_e32 v70, 0x5c00, v2
	global_load_dword v66, v70, s[6:7]
	v_add_u32_e32 v71, 0x400, v2
	global_load_dword v67, v71, s[24:25]
	v_add_u32_e32 v68, 0x200, v3
	v_add_u32_e32 v77, 0x7000, v4
	global_load_dwordx2 v[72:73], v77, s[0:1]
	v_add_u32_e32 v78, 0x6400, v2
	global_load_dword v74, v78, s[6:7]
	v_add_u32_e32 v79, 0xc00, v2
	global_load_dword v75, v79, s[24:25]
	v_add_u32_e32 v76, 0x600, v3
	v_add_u32_e32 v85, 0x8000, v4
	global_load_dwordx2 v[80:81], v85, s[0:1]
	v_add_u32_e32 v86, 0x6c00, v2
	global_load_dword v82, v86, s[6:7]
	v_add_u32_e32 v87, 0x1400, v2
	global_load_dword v83, v87, s[24:25]
	v_add_u32_e32 v84, 0xa00, v3
	v_add_u32_e32 v93, 0x9000, v4
	global_load_dwordx2 v[88:89], v93, s[0:1]
	v_add_u32_e32 v94, 0x7400, v2
	global_load_dword v90, v94, s[6:7]
	v_add_u32_e32 v95, 0x1c00, v2
	global_load_dword v91, v95, s[24:25]
	v_add_u32_e32 v92, 0xe00, v3
	v_add_u32_e32 v101, 0xa000, v4
	global_load_dwordx2 v[96:97], v101, s[0:1]
	v_add_u32_e32 v102, 0x7c00, v2
	global_load_dword v98, v102, s[6:7]
	v_add_u32_e32 v103, 0x2400, v2
	global_load_dword v99, v103, s[24:25]
	v_add_u32_e32 v100, 0x1200, v3
	s_andn2_b64 vcc, exec, s[44:45]
	s_cbranch_vccz .Lfx_wait
	v_add_u32_e32 v61, 0x5000, v4
	global_load_dwordx2 v[56:57], v61, s[0:1]
	v_add_u32_e32 v62, 0x5400, v2
	global_load_dword v58, v62, s[6:7]
	v_add_u32_e32 v63, 0xfffffc00, v2
	global_load_dword v59, v63, s[24:25]
	v_add_u32_e32 v60, 0xfffffe00, v3
.Lfx_wait:
	s_waitcnt vmcnt(0)
	s_and_b64 vcc, exec, s[38:39]
	s_cbranch_vccz .Lfx_cB
	v_fma_f32 v21, v18, v19, v16
	v_fma_f32 v29, v26, v27, v24
	v_fma_f32 v37, v34, v35, v32
	v_fma_f32 v45, v42, v43, v40
	v_fma_f32 v53, v50, v51, v48
	v_mul_f32_e32 v22, 0xbfb8aa3b, v21
	v_mul_f32_e32 v30, 0xbfb8aa3b, v29
	v_mul_f32_e32 v38, 0xbfb8aa3b, v37
	v_mul_f32_e32 v46, 0xbfb8aa3b, v45
	v_mul_f32_e32 v54, 0xbfb8aa3b, v53
	v_exp_f32_e32 v22, v22
	v_exp_f32_e32 v30, v30
	v_exp_f32_e32 v38, v38
	v_exp_f32_e32 v46, v46
	v_exp_f32_e32 v54, v54
	s_nop 0
	v_add_f32_e32 v22, 1.0, v22
	v_add_f32_e32 v30, 1.0, v30
	v_add_f32_e32 v38, 1.0, v38
	v_add_f32_e32 v46, 1.0, v46
	v_add_f32_e32 v54, 1.0, v54
	v_rcp_f32_e32 v22, v22
	v_rcp_f32_e32 v30, v30
	v_rcp_f32_e32 v38, v38
	v_rcp_f32_e32 v46, v46
	v_rcp_f32_e32 v54, v54
	s_nop 0
	v_mul_f32_e32 v21, v21, v22
	v_mul_f32_e32 v29, v29, v30
	v_mul_f32_e32 v37, v37, v38
	v_mul_f32_e32 v45, v45, v46
	v_mul_f32_e32 v53, v53, v54
	v_mul_f32_e32 v21, v17, v21
	v_mul_f32_e32 v29, v25, v29
	v_mul_f32_e32 v37, v33, v37
	v_mul_f32_e32 v45, v41, v45
	v_mul_f32_e32 v53, v49, v53
	v_bfe_u32 v22, v21, 16, 1
	v_bfe_u32 v30, v29, 16, 1
	v_bfe_u32 v38, v37, 16, 1
	v_bfe_u32 v46, v45, 16, 1
	v_bfe_u32 v54, v53, 16, 1
	v_add3_u32 v21, v21, v22, s92
	v_add3_u32 v29, v29, v30, s92
	v_add3_u32 v37, v37, v38, s92
	v_add3_u32 v45, v45, v46, s92
	v_add3_u32 v53, v53, v54, s92
	global_store_short_d16_hi v20, v21, s[18:19]
	global_store_short_d16_hi v28, v29, s[18:19]
	global_store_short_d16_hi v36, v37, s[18:19]
	global_store_short_d16_hi v44, v45, s[18:19]
	global_store_short_d16_hi v52, v53, s[18:19]
	s_and_b64 vcc, exec, s[44:45]
	s_cbranch_vccz .Lfx_cB
	v_fma_f32 v61, v58, v59, v56
	v_mul_f32_e32 v62, 0xbfb8aa3b, v61
	v_exp_f32_e32 v62, v62
	s_nop 0
	v_add_f32_e32 v62, 1.0, v62
	v_rcp_f32_e32 v62, v62
	s_nop 0
	v_mul_f32_e32 v61, v61, v62
	v_mul_f32_e32 v61, v57, v61
	v_bfe_u32 v62, v61, 16, 1
	v_add3_u32 v61, v61, v62, s92
	global_store_short_d16_hi v60, v61, s[18:19]
.Lfx_cB:
	s_andn2_b64 vcc, exec, s[20:21]
	s_cbranch_vccz .Lfx_done
	v_fma_f32 v69, v66, v67, v64
	v_fma_f32 v77, v74, v75, v72
	v_fma_f32 v85, v82, v83, v80
	v_fma_f32 v93, v90, v91, v88
	v_fma_f32 v101, v98, v99, v96
	v_mul_f32_e32 v70, 0xbfb8aa3b, v69
	v_mul_f32_e32 v78, 0xbfb8aa3b, v77
	v_mul_f32_e32 v86, 0xbfb8aa3b, v85
	v_mul_f32_e32 v94, 0xbfb8aa3b, v93
	v_mul_f32_e32 v102, 0xbfb8aa3b, v101
	v_exp_f32_e32 v70, v70
	v_exp_f32_e32 v78, v78
	v_exp_f32_e32 v86, v86
	v_exp_f32_e32 v94, v94
	v_exp_f32_e32 v102, v102
	s_nop 0
	v_add_f32_e32 v70, 1.0, v70
	v_add_f32_e32 v78, 1.0, v78
	v_add_f32_e32 v86, 1.0, v86
	v_add_f32_e32 v94, 1.0, v94
	v_add_f32_e32 v102, 1.0, v102
	v_rcp_f32_e32 v70, v70
	v_rcp_f32_e32 v78, v78
	v_rcp_f32_e32 v86, v86
	v_rcp_f32_e32 v94, v94
	v_rcp_f32_e32 v102, v102
	s_nop 0
	v_mul_f32_e32 v69, v69, v70
	v_mul_f32_e32 v77, v77, v78
	v_mul_f32_e32 v85, v85, v86
	v_mul_f32_e32 v93, v93, v94
	v_mul_f32_e32 v101, v101, v102
	v_mul_f32_e32 v69, v65, v69
	v_mul_f32_e32 v77, v73, v77
	v_mul_f32_e32 v85, v81, v85
	v_mul_f32_e32 v93, v89, v93
	v_mul_f32_e32 v101, v97, v101
	v_bfe_u32 v70, v69, 16, 1
	v_bfe_u32 v78, v77, 16, 1
	v_bfe_u32 v86, v85, 16, 1
	v_bfe_u32 v94, v93, 16, 1
	v_bfe_u32 v102, v101, 16, 1
	v_add3_u32 v69, v69, v70, s92
	v_add3_u32 v77, v77, v78, s92
	v_add3_u32 v85, v85, v86, s92
	v_add3_u32 v93, v93, v94, s92
	v_add3_u32 v101, v101, v102, s92
	global_store_short_d16_hi v68, v69, s[26:27]
	global_store_short_d16_hi v76, v77, s[26:27]
	global_store_short_d16_hi v84, v85, s[26:27]
	global_store_short_d16_hi v92, v93, s[26:27]
	global_store_short_d16_hi v100, v101, s[26:27]
	s_andn2_b64 vcc, exec, s[44:45]
	s_cbranch_vccz .Lfx_done
	v_fma_f32 v61, v58, v59, v56
	v_mul_f32_e32 v62, 0xbfb8aa3b, v61
	v_exp_f32_e32 v62, v62
	s_nop 0
	v_add_f32_e32 v62, 1.0, v62
	v_rcp_f32_e32 v62, v62
	s_nop 0
	v_mul_f32_e32 v61, v61, v62
	v_mul_f32_e32 v61, v57, v61
	v_bfe_u32 v62, v61, 16, 1
	v_add3_u32 v61, v61, v62, s92
	global_store_short_d16_hi v60, v61, s[26:27]
.Lfx_done:
	s_branch .LBB0_783
.LBB0_799:
	s_waitcnt vmcnt(0)
	v_readlane_b32 s6, v255, 10
	v_readlane_b32 s7, v255, 11
	s_mov_b64 s[0:1], 0
	s_and_b64 vcc, exec, s[6:7]
	s_barrier
	s_cbranch_vccz .LBB0_801
	s_load_dwordx2 s[0:1], s[4:5], 0x98
